# GEMM-in k-loop ping-pong between wave halves; scan consumer block: scalar fmac chains instead of packed ops with moves
# speedup vs baseline: 1.1154x; 1.0193x over previous
; template <int AMODE, int BN, class Epi>
; __device__ __forceinline__ void gemm_tile(const bf16_t* A, const int lda, const bf16_t* Bt, const int K, const int m0, const float* mu, char* lds, const Epi& epi) {
;     ...
;   f32x16 acc[MI][2];
; #pragma unroll
;   for (int i = 0; i < MI; ++i)
; #pragma unroll
;     for (int j = 0; j < 2; ++j)
; #pragma unroll
;       for (int r = 0; r < 16; ++r) acc[i][j][r] = 0.f;
;   bf16x8 ra[4], rb[NBR], rp[4], rn[4];
;   float ssq[4] = {0.f, 0.f, 0.f, 0.f};
;   int dprev[4], dnext[4];
;   if constexpr (AMODE == 1) {
;     const int t0 = m0 % TL;
; #pragma unroll
;     for (int i = 0; i < 4; ++i) { const int t = t0 + srow + 64 * i; dprev[i] = (t != 0 && t != T) ? 1 : 0; dnext[i] = (t != T - 1 && t != TL - 1) ? 1 : 0; }
;   }
;   auto gload = [&](int k0) {
; #pragma unroll
;     for (int i = 0; i < 4; ++i) {
;       const bf16_t* ap = A + (size_t)(m0 + srow + 64 * i) * lda + k0 + scc;
;       ra[i] = *(const bf16x8*)ap;
;       if constexpr (AMODE == 1) { rp[i] = *(const bf16x8*)(ap - dprev[i] * lda); rn[i] = *(const bf16x8*)(ap + dnext[i] * lda); }
;     }
; #pragma unroll
;     for (int i = 0; i < NBR; ++i) rb[i] = *(const bf16x8*)(Bt + (size_t)browi[i] * K + k0 + scc);
;   };
;     ...
;   const int nk = K >> 6;
;   gload(0);
;   lstore(0, 0);
;   if (nk > 1) gload(64);
;   __syncthreads();
.LBB0_407:
	v_or_b32_e32 v0, s20, v161
	v_ashrrev_i32_e32 v1, 31, v0
	v_lshlrev_b64 v[48:49], 11, v[0:1]
	v_lshl_add_u64 v[2:3], s[16:17], 0, v[48:49]
	v_lshl_add_u64 v[52:53], v[48:49], 0, s[14:15]
	s_lshl_b32 s18, s48, 8
	v_lshl_add_u64 v[50:51], v[2:3], 0, v[170:171]
	v_lshl_add_u64 v[2:3], s[16:17], 0, v[52:53]
	s_and_b32 s21, s18, 0x300
	s_lshl_b32 s18, s4, 10
	v_lshl_add_u64 v[54:55], v[2:3], 0, v[170:171]
	v_or_b32_e32 v2, 0x80, v0
	v_add_u32_e32 v0, 0xc0, v0
	s_or_b32 s18, s21, s18
	v_ashrrev_i32_e32 v1, 31, v0
	s_ashr_i32 s19, s18, 31
	v_lshlrev_b64 v[60:61], 11, v[0:1]
	s_lshl_b64 s[18:19], s[18:19], 11
	v_lshl_add_u64 v[0:1], s[16:17], 0, v[60:61]
	v_lshl_add_u64 v[62:63], v[0:1], 0, v[170:171]
	v_lshl_add_u64 v[0:1], v[164:165], 0, s[18:19]
	v_lshl_add_u64 v[64:65], v[0:1], 0, v[170:171]
	v_add_co_u32_e32 v66, vcc, s34, v64
	v_ashrrev_i32_e32 v3, 31, v2
	s_nop 0
	v_addc_co_u32_e32 v67, vcc, 0, v65, vcc
	v_add_co_u32_e32 v68, vcc, s35, v64
	v_lshlrev_b64 v[56:57], 11, v[2:3]
	s_nop 0
	v_addc_co_u32_e32 v69, vcc, 0, v65, vcc
	v_lshl_add_u64 v[2:3], s[16:17], 0, v[56:57]
	v_add_co_u32_e32 v70, vcc, s43, v64
	v_lshl_add_u64 v[58:59], v[2:3], 0, v[170:171]
	s_nop 0
	v_addc_co_u32_e32 v71, vcc, 0, v65, vcc
	global_load_dwordx4 v[16:19], v[50:51], off
	global_load_dwordx4 v[128:131], v[50:51], off offset:128
	global_load_dwordx4 v[20:23], v[54:55], off
	global_load_dwordx4 v[24:27], v[58:59], off
	global_load_dwordx4 v[28:31], v[62:63], off
	global_load_dwordx4 v[32:35], v[64:65], off
	global_load_dwordx4 v[36:39], v[66:67], off
	global_load_dwordx4 v[40:43], v[68:69], off
	global_load_dwordx4 v[44:47], v[70:71], off
	global_load_dwordx4 v[132:135], v[54:55], off offset:128
	global_load_dwordx4 v[136:139], v[58:59], off offset:128
	global_load_dwordx4 v[140:143], v[62:63], off offset:128
	global_load_dwordx4 v[144:147], v[64:65], off offset:128
	global_load_dwordx4 v[148:151], v[66:67], off offset:128
	global_load_dwordx4 v[152:155], v[68:69], off offset:128
	global_load_dwordx4 v[156:159], v[70:71], off offset:128
	v_lshl_add_u64 v[72:73], s[16:17], 0, v[168:169]
	v_mov_b32_e32 v0, 0
	s_mov_b32 s22, 0
	s_mov_b64 s[16:17], 0
	v_mov_b32_e32 v1, v0
	v_mov_b32_e32 v2, v0
	v_mov_b32_e32 v3, v0
	v_mov_b32_e32 v4, v0
	v_mov_b32_e32 v5, v0
	v_mov_b32_e32 v6, v0
	v_mov_b32_e32 v7, v0
	v_mov_b32_e32 v8, v0
	v_mov_b32_e32 v9, v0
	v_mov_b32_e32 v10, v0
	v_mov_b32_e32 v11, v0
	v_mov_b32_e32 v12, v0
	v_mov_b32_e32 v13, v0
	v_mov_b32_e32 v14, v0
	v_mov_b32_e32 v15, v0
	v_lshl_add_u64 v[194:195], v[72:73], 0, v[48:49]
	v_lshl_add_u64 v[196:197], v[72:73], 0, v[60:61]
	v_lshl_add_u64 v[198:199], v[72:73], 0, v[56:57]
	v_lshl_add_u64 v[200:201], v[72:73], 0, v[52:53]
	v_lshl_add_u64 v[202:203], v[166:167], 0, s[18:19]
	v_mov_b32_e32 v48, v0
	v_mov_b32_e32 v49, v0
	v_mov_b32_e32 v50, v0
	v_mov_b32_e32 v51, v0
	v_mov_b32_e32 v52, v0
	v_mov_b32_e32 v53, v0
	v_mov_b32_e32 v54, v0
	v_mov_b32_e32 v55, v0
	v_mov_b32_e32 v56, v0
	v_mov_b32_e32 v57, v0
	v_mov_b32_e32 v58, v0
	v_mov_b32_e32 v59, v0
	v_mov_b32_e32 v60, v0
	v_mov_b32_e32 v61, v0
	v_mov_b32_e32 v62, v0
	v_mov_b32_e32 v63, v0
	v_mov_b32_e32 v64, v0
	v_mov_b32_e32 v65, v0
	s_waitcnt vmcnt(15)
	ds_write_b128 v185, v[16:19]
	s_waitcnt vmcnt(13)
	ds_write_b128 v185, v[20:23] offset:9216
	s_waitcnt vmcnt(12)
	ds_write_b128 v185, v[24:27] offset:18432
	s_waitcnt vmcnt(11)
	ds_write_b128 v185, v[28:31] offset:27648
	s_waitcnt vmcnt(10)
	ds_write_b128 v185, v[32:35] offset:36864
	s_waitcnt vmcnt(9)
	ds_write_b128 v185, v[36:39] offset:46080
	s_waitcnt vmcnt(8)
	ds_write_b128 v185, v[40:43] offset:55296
	s_waitcnt vmcnt(7)
	ds_write_b128 v185, v[44:47] offset:64512
	v_mov_b32_e32 v16, v0
	v_mov_b32_e32 v17, v0
	v_mov_b32_e32 v18, v0
	v_mov_b32_e32 v19, v0
	v_mov_b32_e32 v20, v0
	v_mov_b32_e32 v21, v0
	v_mov_b32_e32 v22, v0
	v_mov_b32_e32 v23, v0
	v_mov_b32_e32 v24, v0
	v_mov_b32_e32 v25, v0
	v_mov_b32_e32 v26, v0
	v_mov_b32_e32 v27, v0
	v_mov_b32_e32 v28, v0
	v_mov_b32_e32 v29, v0
	v_mov_b32_e32 v30, v0
	v_mov_b32_e32 v31, v0
	v_mov_b32_e32 v32, v0
	v_mov_b32_e32 v33, v0
	v_mov_b32_e32 v34, v0
	v_mov_b32_e32 v35, v0
	v_mov_b32_e32 v36, v0
	v_mov_b32_e32 v37, v0
	v_mov_b32_e32 v38, v0
	v_mov_b32_e32 v39, v0
	v_mov_b32_e32 v40, v0
	v_mov_b32_e32 v41, v0
	v_mov_b32_e32 v42, v0
	v_mov_b32_e32 v43, v0
	v_mov_b32_e32 v44, v0
	v_mov_b32_e32 v45, v0
	v_mov_b32_e32 v46, v0
	v_mov_b32_e32 v47, v0
	v_mov_b32_e32 v66, v0
	v_mov_b32_e32 v67, v0
	v_mov_b32_e32 v68, v0
	v_mov_b32_e32 v69, v0
	v_mov_b32_e32 v70, v0
	v_mov_b32_e32 v71, v0
	v_mov_b32_e32 v72, v0
	v_mov_b32_e32 v73, v0
	v_mov_b32_e32 v74, v0
	v_mov_b32_e32 v75, v0
	v_mov_b32_e32 v76, v0
	v_mov_b32_e32 v77, v0
	v_mov_b32_e32 v78, v0
	v_mov_b32_e32 v79, v0
	v_mov_b32_e32 v80, v0
	v_mov_b32_e32 v81, v0
	v_mov_b32_e32 v82, v0
	v_mov_b32_e32 v83, v0
	v_mov_b32_e32 v84, v0
	v_mov_b32_e32 v85, v0
	v_mov_b32_e32 v86, v0
	v_mov_b32_e32 v87, v0
	v_mov_b32_e32 v88, v0
	v_mov_b32_e32 v89, v0
	v_mov_b32_e32 v90, v0
	v_mov_b32_e32 v91, v0
	v_mov_b32_e32 v92, v0
	v_mov_b32_e32 v93, v0
	v_mov_b32_e32 v94, v0
	v_mov_b32_e32 v95, v0
	v_mov_b32_e32 v96, v0
	v_mov_b32_e32 v97, v0
	v_mov_b32_e32 v98, v0
	v_mov_b32_e32 v99, v0
	v_mov_b32_e32 v100, v0
	v_mov_b32_e32 v101, v0
	v_mov_b32_e32 v102, v0
	v_mov_b32_e32 v103, v0
	v_mov_b32_e32 v104, v0
	v_mov_b32_e32 v105, v0
	v_mov_b32_e32 v106, v0
	v_mov_b32_e32 v107, v0
	v_mov_b32_e32 v108, v0
	v_mov_b32_e32 v109, v0
	v_mov_b32_e32 v110, v0
	v_mov_b32_e32 v111, v0
	v_mov_b32_e32 v112, v0
	v_mov_b32_e32 v113, v0
	v_mov_b32_e32 v114, v0
	v_mov_b32_e32 v115, v0
	v_mov_b32_e32 v116, v0
	v_mov_b32_e32 v117, v0
	v_mov_b32_e32 v118, v0
	v_mov_b32_e32 v119, v0
	v_mov_b32_e32 v120, v0
	v_mov_b32_e32 v121, v0
	v_mov_b32_e32 v122, v0
	v_mov_b32_e32 v123, v0
	v_mov_b32_e32 v124, v0
	v_mov_b32_e32 v125, v0
	v_mov_b32_e32 v126, v0
	v_mov_b32_e32 v127, v0
	s_waitcnt lgkmcnt(0)
	s_barrier
	v_readfirstlane_b32 s61, v178
	s_nop 0
	s_cmpk_lt_u32 s61, 0x100
	s_cbranch_scc0 .LppP2_B
; __device__ __forceinline__ float lo16(unsigned w) { return __uint_as_float(w << 16); }
; __device__ __forceinline__ float hi16(unsigned w) { return __uint_as_float(w & 0xffff0000u); }
; #define MFMA(a, b, c) __builtin_amdgcn_mfma_f32_32x32x16_bf16((a), (b), (c), 0, 0, 0)
; template <int AMODE, int BN, class Epi>
; __device__ __forceinline__ void gemm_tile(const bf16_t* A, const int lda, const bf16_t* Bt, const int K, const int m0, const float* mu, char* lds, const Epi& epi) {
;     ...
; #pragma unroll
;       for (int i = 0; i < 4; ++i) {
;         *(bf16x8*)(base + (srow + 64 * i) * G_LDT + scc * 2) = ra[i];
;         if constexpr (AMODE == 2) {
;           const u32x4 hc = *(const u32x4*)&ra[i];
; #pragma unroll
;           for (int q = 0; q < 4; ++q) { const float c0 = lo16(hc[q]), c1 = hi16(hc[q]); ssq[i] += c0 * c0 + c1 * c1; }
;         }
;       }
;     }
; #pragma unroll
;     for (int i = 0; i < NBR; ++i) *(bf16x8*)(base + 256 * G_LDT + (srow + 64 * i) * G_LDT + scc * 2) = rb[i];
;     ...
;     {
;       const char* Ab = lds + s * G_STAGE + (wm * (32 * MI) + r32) * G_LDT + hi * 16;
;       const char* Bb = lds + s * G_STAGE + 256 * G_LDT + (wn * 64 + r32) * G_LDT + hi * 16;
;       bf16x8 fb[2][2], fa[2][MI];
;       fb[0][0] = *(const bf16x8*)(Bb); fb[0][1] = *(const bf16x8*)(Bb + 32 * G_LDT);
; #pragma unroll
;       for (int mi = 0; mi < MI; ++mi) fa[0][mi] = *(const bf16x8*)(Ab + mi * 32 * G_LDT);
; #pragma unroll
;       for (int ks = 0; ks < 4; ++ks) {
;         const int sl = ks & 1;
;         if (ks + 1 < 4) {
;           fb[sl ^ 1][0] = *(const bf16x8*)(Bb + (ks + 1) * 32); fb[sl ^ 1][1] = *(const bf16x8*)(Bb + 32 * G_LDT + (ks + 1) * 32);
; #pragma unroll
;           for (int mi = 0; mi < MI; ++mi) fa[sl ^ 1][mi] = *(const bf16x8*)(Ab + mi * 32 * G_LDT + (ks + 1) * 32);
;         }
; #pragma unroll
;         for (int mi = 0; mi < MI; ++mi) { acc[mi][0] = MFMA(fb[sl][0], fa[sl][mi], acc[mi][0]); acc[mi][1] = MFMA(fb[sl][1], fa[sl][mi], acc[mi][1]); }
;       }
;     }
.LppP2_A:
	s_and_b32 s18, s22, 1
	s_mul_i32 s18, s18, 0x12000
	s_add_i32 s18, s18, 0
	v_add3_u32 v173, s18, v205, v177
	ds_read_b128 v[212:215], v173 offset:36864
	v_add3_u32 v175, s18, v204, v177
	ds_read_b128 v[216:219], v175
	ds_read_b128 v[220:223], v173 offset:36896
	ds_read_b128 v[228:231], v175 offset:32
	ds_read_b128 v[232:235], v173 offset:41472
	ds_read_b128 v[236:239], v173 offset:41504
	s_waitcnt lgkmcnt(1)
	v_mfma_f32_32x32x16_bf16 v[96:111], v[232:235], v[216:219], v[96:111]
	v_mfma_f32_32x32x16_bf16 v[112:127], v[212:215], v[216:219], v[112:127]
	ds_read_b128 v[216:219], v175 offset:4608
	ds_read_b128 v[240:243], v175 offset:4640
	s_waitcnt lgkmcnt(1)
	v_mfma_f32_32x32x16_bf16 v[80:95], v[212:215], v[216:219], v[80:95]
	v_mfma_f32_32x32x16_bf16 v[64:79], v[232:235], v[216:219], v[64:79]
	ds_read_b128 v[216:219], v175 offset:9216
	ds_read_b128 v[244:247], v175 offset:9248
	s_waitcnt lgkmcnt(1)
	v_mfma_f32_32x32x16_bf16 v[48:63], v[212:215], v[216:219], v[48:63]
	v_mfma_f32_32x32x16_bf16 v[32:47], v[232:235], v[216:219], v[32:47]
	ds_read_b128 v[216:219], v175 offset:13824
	ds_read_b128 v[248:251], v175 offset:13856
	s_waitcnt lgkmcnt(1)
	v_mfma_f32_32x32x16_bf16 v[16:31], v[212:215], v[216:219], v[16:31]
	v_mfma_f32_32x32x16_bf16 v[0:15], v[232:235], v[216:219], v[0:15]
	v_mfma_f32_32x32x16_bf16 v[112:127], v[220:223], v[228:231], v[112:127]
	v_mfma_f32_32x32x16_bf16 v[96:111], v[236:239], v[228:231], v[96:111]
	v_mfma_f32_32x32x16_bf16 v[80:95], v[220:223], v[240:243], v[80:95]
	v_mfma_f32_32x32x16_bf16 v[64:79], v[236:239], v[240:243], v[64:79]
	v_mfma_f32_32x32x16_bf16 v[48:63], v[220:223], v[244:247], v[48:63]
	v_mfma_f32_32x32x16_bf16 v[32:47], v[236:239], v[244:247], v[32:47]
	s_waitcnt lgkmcnt(0)
	v_mfma_f32_32x32x16_bf16 v[16:31], v[220:223], v[248:251], v[16:31]
	ds_read_b128 v[212:215], v173 offset:36928
	ds_read_b128 v[216:219], v175 offset:64
	ds_read_b128 v[220:223], v173 offset:36960
	ds_read_b128 v[228:231], v175 offset:96
	v_mfma_f32_32x32x16_bf16 v[0:15], v[236:239], v[248:251], v[0:15]
	ds_read_b128 v[232:235], v173 offset:41536
	ds_read_b128 v[236:239], v173 offset:41568
	s_waitcnt lgkmcnt(4)
	v_mfma_f32_32x32x16_bf16 v[112:127], v[212:215], v[216:219], v[112:127]
	s_waitcnt lgkmcnt(1)
	v_mfma_f32_32x32x16_bf16 v[96:111], v[232:235], v[216:219], v[96:111]
	ds_read_b128 v[216:219], v175 offset:4672
	ds_read_b128 v[240:243], v175 offset:4704
	s_waitcnt lgkmcnt(1)
	v_mfma_f32_32x32x16_bf16 v[80:95], v[212:215], v[216:219], v[80:95]
	v_mfma_f32_32x32x16_bf16 v[64:79], v[232:235], v[216:219], v[64:79]
	ds_read_b128 v[216:219], v175 offset:9280
	ds_read_b128 v[244:247], v175 offset:9312
	s_waitcnt lgkmcnt(1)
	v_mfma_f32_32x32x16_bf16 v[48:63], v[212:215], v[216:219], v[48:63]
	v_mfma_f32_32x32x16_bf16 v[32:47], v[232:235], v[216:219], v[32:47]
	ds_read_b128 v[216:219], v175 offset:13888
	ds_read_b128 v[248:251], v175 offset:13920
	s_waitcnt lgkmcnt(0)
	s_barrier
	v_mfma_f32_32x32x16_bf16 v[16:31], v[212:215], v[216:219], v[16:31]
	v_mfma_f32_32x32x16_bf16 v[0:15], v[232:235], v[216:219], v[0:15]
	v_mfma_f32_32x32x16_bf16 v[112:127], v[220:223], v[228:231], v[112:127]
	v_mfma_f32_32x32x16_bf16 v[96:111], v[236:239], v[228:231], v[96:111]
	v_mfma_f32_32x32x16_bf16 v[80:95], v[220:223], v[240:243], v[80:95]
	v_mfma_f32_32x32x16_bf16 v[64:79], v[236:239], v[240:243], v[64:79]
	v_mfma_f32_32x32x16_bf16 v[48:63], v[220:223], v[244:247], v[48:63]
	v_mfma_f32_32x32x16_bf16 v[32:47], v[236:239], v[244:247], v[32:47]
	v_mfma_f32_32x32x16_bf16 v[16:31], v[220:223], v[248:251], v[16:31]
	v_mfma_f32_32x32x16_bf16 v[0:15], v[236:239], v[248:251], v[0:15]
	s_and_b32 s18, s22, 1
	s_cmpk_eq_i32 s16, 0x780
	s_cbranch_scc1 .LppP2_nowA
	s_xor_b32 s19, s18, 1
	s_mul_i32 s19, s19, 0x12000
	v_add_u32_e32 v173, s19, v185
	s_waitcnt vmcnt(7)
	ds_write_b128 v173, v[128:131]
	s_waitcnt vmcnt(6)
	ds_write_b128 v173, v[132:135] offset:9216
	s_waitcnt vmcnt(5)
	ds_write_b128 v173, v[136:139] offset:18432
	s_waitcnt vmcnt(4)
	ds_write_b128 v173, v[140:143] offset:27648
	s_waitcnt vmcnt(3)
	ds_write_b128 v173, v[144:147] offset:36864
	s_waitcnt vmcnt(2)
	ds_write_b128 v173, v[148:151] offset:46080
	s_waitcnt vmcnt(1)
	ds_write_b128 v173, v[152:155] offset:55296
	s_waitcnt vmcnt(0)
	ds_write_b128 v173, v[156:159] offset:64512

; #define MFMA(a, b, c) __builtin_amdgcn_mfma_f32_32x32x16_bf16((a), (b), (c), 0, 0, 0)
; template <int AMODE, int BN, class Epi>
; __device__ __forceinline__ void gemm_tile(const bf16_t* A, const int lda, const bf16_t* Bt, const int K, const int m0, const float* mu, char* lds, const Epi& epi) {
;     ...
;   for (int kt = 0; kt < nk; ++kt) {
;     const int s = kt & 1;
;     if (kt + 1 < nk) lstore(s ^ 1, (kt + 1) * 64);
;     if (kt + 2 < nk) gload((kt + 2) * 64);
;     {
;       const char* Ab = lds + s * G_STAGE + (wm * (32 * MI) + r32) * G_LDT + hi * 16;
;       const char* Bb = lds + s * G_STAGE + 256 * G_LDT + (wn * 64 + r32) * G_LDT + hi * 16;
;       bf16x8 fb[2][2], fa[2][MI];
;       fb[0][0] = *(const bf16x8*)(Bb); fb[0][1] = *(const bf16x8*)(Bb + 32 * G_LDT);
; #pragma unroll
;       for (int mi = 0; mi < MI; ++mi) fa[0][mi] = *(const bf16x8*)(Ab + mi * 32 * G_LDT);
; #pragma unroll
;       for (int ks = 0; ks < 4; ++ks) {
;         const int sl = ks & 1;
;         if (ks + 1 < 4) {
;           fb[sl ^ 1][0] = *(const bf16x8*)(Bb + (ks + 1) * 32); fb[sl ^ 1][1] = *(const bf16x8*)(Bb + 32 * G_LDT + (ks + 1) * 32);
; #pragma unroll
;           for (int mi = 0; mi < MI; ++mi) fa[sl ^ 1][mi] = *(const bf16x8*)(Ab + mi * 32 * G_LDT + (ks + 1) * 32);
;         }
; #pragma unroll
;         for (int mi = 0; mi < MI; ++mi) { acc[mi][0] = MFMA(fb[sl][0], fa[sl][mi], acc[mi][0]); acc[mi][1] = MFMA(fb[sl][1], fa[sl][mi], acc[mi][1]); }
;       }
;     }
;     __syncthreads();
;   }
.LppP2_nogA:
	s_waitcnt lgkmcnt(0)
	s_barrier
	s_add_u32 s16, s16, 0x80
	s_addc_u32 s17, s17, 0
	s_add_i32 s22, s22, 1
	s_cmpk_lg_i32 s16, 0x800
	s_cbranch_scc1 .LppP2_A
	s_branch .LBB0_394

; #define MFMA(a, b, c) __builtin_amdgcn_mfma_f32_32x32x16_bf16((a), (b), (c), 0, 0, 0)
; template <int AMODE, int BN, class Epi>
; __device__ __forceinline__ void gemm_tile(const bf16_t* A, const int lda, const bf16_t* Bt, const int K, const int m0, const float* mu, char* lds, const Epi& epi) {
;     ...
;     {
;       const char* Ab = lds + s * G_STAGE + (wm * (32 * MI) + r32) * G_LDT + hi * 16;
;       const char* Bb = lds + s * G_STAGE + 256 * G_LDT + (wn * 64 + r32) * G_LDT + hi * 16;
;       bf16x8 fb[2][2], fa[2][MI];
;       fb[0][0] = *(const bf16x8*)(Bb); fb[0][1] = *(const bf16x8*)(Bb + 32 * G_LDT);
; #pragma unroll
;       for (int mi = 0; mi < MI; ++mi) fa[0][mi] = *(const bf16x8*)(Ab + mi * 32 * G_LDT);
; #pragma unroll
;       for (int ks = 0; ks < 4; ++ks) {
;         const int sl = ks & 1;
;         if (ks + 1 < 4) {
;           fb[sl ^ 1][0] = *(const bf16x8*)(Bb + (ks + 1) * 32); fb[sl ^ 1][1] = *(const bf16x8*)(Bb + 32 * G_LDT + (ks + 1) * 32);
; #pragma unroll
;           for (int mi = 0; mi < MI; ++mi) fa[sl ^ 1][mi] = *(const bf16x8*)(Ab + mi * 32 * G_LDT + (ks + 1) * 32);
;         }
; #pragma unroll
;         for (int mi = 0; mi < MI; ++mi) { acc[mi][0] = MFMA(fb[sl][0], fa[sl][mi], acc[mi][0]); acc[mi][1] = MFMA(fb[sl][1], fa[sl][mi], acc[mi][1]); }
;       }
;     }
;     __syncthreads();
.LppP2_nogB:
	s_waitcnt lgkmcnt(0)
	s_barrier
	s_and_b32 s18, s22, 1
	s_mul_i32 s18, s18, 0x12000
	s_add_i32 s18, s18, 0
	v_add3_u32 v173, s18, v205, v177
	ds_read_b128 v[212:215], v173 offset:36864
	v_add3_u32 v175, s18, v204, v177
	ds_read_b128 v[216:219], v175
	ds_read_b128 v[220:223], v173 offset:36896
	ds_read_b128 v[228:231], v175 offset:32
	ds_read_b128 v[232:235], v173 offset:41472
	ds_read_b128 v[236:239], v173 offset:41504
	s_waitcnt lgkmcnt(1)
	v_mfma_f32_32x32x16_bf16 v[96:111], v[232:235], v[216:219], v[96:111]
	v_mfma_f32_32x32x16_bf16 v[112:127], v[212:215], v[216:219], v[112:127]
	ds_read_b128 v[216:219], v175 offset:4608
	ds_read_b128 v[240:243], v175 offset:4640
	s_waitcnt lgkmcnt(1)
	v_mfma_f32_32x32x16_bf16 v[80:95], v[212:215], v[216:219], v[80:95]
	v_mfma_f32_32x32x16_bf16 v[64:79], v[232:235], v[216:219], v[64:79]
	ds_read_b128 v[216:219], v175 offset:9216
	ds_read_b128 v[244:247], v175 offset:9248
	s_waitcnt lgkmcnt(1)
	v_mfma_f32_32x32x16_bf16 v[48:63], v[212:215], v[216:219], v[48:63]
	v_mfma_f32_32x32x16_bf16 v[32:47], v[232:235], v[216:219], v[32:47]
	ds_read_b128 v[216:219], v175 offset:13824
	ds_read_b128 v[248:251], v175 offset:13856
	s_waitcnt lgkmcnt(1)
	v_mfma_f32_32x32x16_bf16 v[16:31], v[212:215], v[216:219], v[16:31]
	v_mfma_f32_32x32x16_bf16 v[0:15], v[232:235], v[216:219], v[0:15]
	v_mfma_f32_32x32x16_bf16 v[112:127], v[220:223], v[228:231], v[112:127]
	v_mfma_f32_32x32x16_bf16 v[96:111], v[236:239], v[228:231], v[96:111]
	v_mfma_f32_32x32x16_bf16 v[80:95], v[220:223], v[240:243], v[80:95]
	v_mfma_f32_32x32x16_bf16 v[64:79], v[236:239], v[240:243], v[64:79]
	v_mfma_f32_32x32x16_bf16 v[48:63], v[220:223], v[244:247], v[48:63]
	v_mfma_f32_32x32x16_bf16 v[32:47], v[236:239], v[244:247], v[32:47]
	s_waitcnt lgkmcnt(0)
	v_mfma_f32_32x32x16_bf16 v[16:31], v[220:223], v[248:251], v[16:31]
	ds_read_b128 v[212:215], v173 offset:36928
	ds_read_b128 v[216:219], v175 offset:64
	ds_read_b128 v[220:223], v173 offset:36960
	ds_read_b128 v[228:231], v175 offset:96
	v_mfma_f32_32x32x16_bf16 v[0:15], v[236:239], v[248:251], v[0:15]
	ds_read_b128 v[232:235], v173 offset:41536
	ds_read_b128 v[236:239], v173 offset:41568
	s_waitcnt lgkmcnt(4)
	v_mfma_f32_32x32x16_bf16 v[112:127], v[212:215], v[216:219], v[112:127]
	s_waitcnt lgkmcnt(1)
	v_mfma_f32_32x32x16_bf16 v[96:111], v[232:235], v[216:219], v[96:111]
	ds_read_b128 v[216:219], v175 offset:4672
	ds_read_b128 v[240:243], v175 offset:4704
	s_waitcnt lgkmcnt(1)
	v_mfma_f32_32x32x16_bf16 v[80:95], v[212:215], v[216:219], v[80:95]
	v_mfma_f32_32x32x16_bf16 v[64:79], v[232:235], v[216:219], v[64:79]
	ds_read_b128 v[216:219], v175 offset:9280
	ds_read_b128 v[244:247], v175 offset:9312
	s_waitcnt lgkmcnt(1)
	v_mfma_f32_32x32x16_bf16 v[48:63], v[212:215], v[216:219], v[48:63]
	v_mfma_f32_32x32x16_bf16 v[32:47], v[232:235], v[216:219], v[32:47]
	ds_read_b128 v[216:219], v175 offset:13888
	ds_read_b128 v[248:251], v175 offset:13920
	s_waitcnt lgkmcnt(0)
	s_barrier
	v_mfma_f32_32x32x16_bf16 v[16:31], v[212:215], v[216:219], v[16:31]
	v_mfma_f32_32x32x16_bf16 v[0:15], v[232:235], v[216:219], v[0:15]
	v_mfma_f32_32x32x16_bf16 v[112:127], v[220:223], v[228:231], v[112:127]
	v_mfma_f32_32x32x16_bf16 v[96:111], v[236:239], v[228:231], v[96:111]
	v_mfma_f32_32x32x16_bf16 v[80:95], v[220:223], v[240:243], v[80:95]
	v_mfma_f32_32x32x16_bf16 v[64:79], v[236:239], v[240:243], v[64:79]
	v_mfma_f32_32x32x16_bf16 v[48:63], v[220:223], v[244:247], v[48:63]
	v_mfma_f32_32x32x16_bf16 v[32:47], v[236:239], v[244:247], v[32:47]
	v_mfma_f32_32x32x16_bf16 v[16:31], v[220:223], v[248:251], v[16:31]
	v_mfma_f32_32x32x16_bf16 v[0:15], v[236:239], v[248:251], v[0:15]
	s_add_u32 s16, s16, 0x80
	s_addc_u32 s17, s17, 0
	s_add_i32 s22, s22, 1
	s_cmpk_lg_i32 s16, 0x800
	s_cbranch_scc1 .LppP2_B
	s_branch .LBB0_394

; __device__ __forceinline__ unsigned cvtpk(float lo, float hi) { f32x2 v = {lo, hi}; bf16x2_t b = __builtin_convertvector(v, bf16x2_t); return *(unsigned*)&b; }
; #define MFMA16(a, b, c) __builtin_amdgcn_mfma_f32_16x16x32_bf16((a), (b), (c), 0, 0, 0)
; __device__ void phase_scan(const Params& p, char* lds) {
;     ...
;           u32x4 b1 = {cvtpk(St0[0], St0[1]), cvtpk(St0[2], St0[3]), cvtpk(St1[0], St1[1]), cvtpk(St1[2], St1[3])};
;           u32x4 b2 = {cvtpk(St2[0], St2[1]), cvtpk(St2[2], St2[3]), cvtpk(St3[0], St3[1]), cvtpk(St3[2], St3[3])};
;           f32x4 sr = {0.f, 0.f, 0.f, 0.f}, yr = sr;
;           sr = MFMA16(*(bf16x8*)&cur.aa0, *(bf16x8*)&b1, sr); yr = MFMA16(*(bf16x8*)&cur.ar0, *(bf16x8*)&b1, yr);
;           sr = MFMA16(*(bf16x8*)&cur.aa1, *(bf16x8*)&b2, sr); yr = MFMA16(*(bf16x8*)&cur.ar1, *(bf16x8*)&b2, yr);
;           const float v1 = cur.v[0], v2 = cur.v[1], v3 = cur.v[2], v4 = cur.v[3];
;           const f32x4 s0 = cur.s[0], s1 = cur.s[1], s2 = cur.s[2], s3 = cur.s[3], s4 = cur.s[4], s5 = cur.s[5], s6 = cur.s[6], s7 = cur.s[7];
;           const float sa1 = sr[0];
;           const float sa2 = sr[1] + s0[0] * sa1 + s1[2] * v1;
;           const float sa3 = sr[2] + s0[1] * sa1 + s1[3] * v1 + s0[2] * sa2 + s2[0] * v2;
;           const float sa4 = sr[3] + s0[3] * sa1 + s2[1] * v1 + s1[0] * sa2 + s2[2] * v2 + s1[1] * sa3 + s2[3] * v3;
;           f32x4 y;
;           y[0] = yr[0] + s3[0] * sa1 + s5[2] * v1;
;           y[1] = yr[1] + s3[1] * sa1 + s5[3] * v1 + s3[2] * sa2 + s6[0] * v2;
;           y[2] = yr[2] + s3[3] * sa1 + s6[1] * v1 + s4[0] * sa2 + s6[2] * v2 + s4[1] * sa3 + s6[3] * v3;
;           y[3] = yr[3] + s4[2] * sa1 + s7[0] * v1 + s4[3] * sa2 + s7[1] * v2 + s5[0] * sa3 + s7[2] * v3 + s5[1] * sa4 + s7[3] * v4;
;           u32x4 bu = {cvtpk(sa1, v1), cvtpk(sa2, v2), cvtpk(sa3, v3), cvtpk(sa4, v4)};
;           if (q != 0) { bu[0] = 0u; bu[1] = 0u; bu[2] = 0u; bu[3] = 0u; }
;           St0 = MFMA16(*(bf16x8*)&cur.k0, *(bf16x8*)&bu, St0);
;           St1 = MFMA16(*(bf16x8*)&cur.k1, *(bf16x8*)&bu, St1);
;           St2 = MFMA16(*(bf16x8*)&cur.k2, *(bf16x8*)&bu, St2);
;           St3 = MFMA16(*(bf16x8*)&cur.k3, *(bf16x8*)&bu, St3);
;           *(f32x4*)(yb + blk * 1024) = y;
.LBB0_581:
	v_cvt_pk_bf16_f32 v110, v70, v71
	v_cvt_pk_bf16_f32 v111, v72, v73
	v_cvt_pk_bf16_f32 v112, v74, v75
	v_cvt_pk_bf16_f32 v113, v76, v77
	v_cvt_pk_bf16_f32 v224, v78, v79
	v_cvt_pk_bf16_f32 v225, v80, v81
	s_waitcnt lgkmcnt(14)
	v_mfma_f32_16x16x32_bf16 v[66:69], v[66:69], v[110:113], 0
	v_cvt_pk_bf16_f32 v226, v82, v83
	v_cvt_pk_bf16_f32 v227, v84, v85
	v_add_u32_e32 v86, 0, v234
	v_mfma_f32_16x16x32_bf16 v[62:65], v[62:65], v[110:113], 0
	v_add_u32_e32 v235, 0, v175
	ds_read_b128 v[236:239], v86
	ds_read_b128 v[240:243], v86 offset:64
	ds_read_b128 v[244:247], v86 offset:4096
	ds_read_b128 v[248:251], v86 offset:4160
	v_add_u32_e32 v86, 0, v233
	v_mfma_f32_16x16x32_bf16 v[58:61], v[58:61], v[224:227], v[66:69]
	v_add_u32_e32 v94, 0, v222
	v_add_u32_e32 v118, 0, v16
	ds_read_b128 v[102:105], v86
	ds_read_b128 v[98:101], v86 offset:256
	ds_read_b128 v[90:93], v86 offset:512
	ds_read_b128 v[86:89], v86 offset:768
	s_waitcnt lgkmcnt(14)
	v_mfma_f32_16x16x32_bf16 v[54:57], v[54:57], v[224:227], v[62:65]
	ds_read_b128 v[94:97], v94
	ds_read_b128 v[134:137], v118
	ds_read_b128 v[122:125], v118 offset:16
	ds_read_b128 v[126:129], v118 offset:32
	v_fmac_f32_e32 v59, v50, v58
	v_fmac_f32_e32 v59, v40, v18
	v_fmac_f32_e32 v60, v51, v58
	v_fmac_f32_e32 v60, v41, v18
	v_fmac_f32_e32 v61, v53, v58
	v_fmac_f32_e32 v61, v43, v18
	v_fmac_f32_e32 v60, v52, v59
	v_fmac_f32_e32 v60, v42, v19
	v_fmac_f32_e32 v61, v38, v59
	v_fmac_f32_e32 v61, v44, v19
	v_fmac_f32_e32 v61, v39, v60
	v_fmac_f32_e32 v61, v45, v20
	v_cvt_pk_bf16_f32 v62, v58, v18
	v_cvt_pk_bf16_f32 v63, v59, v19
	v_cvt_pk_bf16_f32 v64, v60, v20
	v_cvt_pk_bf16_f32 v65, v61, v21
	s_waitcnt lgkmcnt(14)
	v_cndmask_b32_e64 v38, 0, v62, s[20:21]
	v_cndmask_b32_e64 v39, 0, v63, s[20:21]
	v_cndmask_b32_e64 v40, 0, v64, s[20:21]
	v_cndmask_b32_e64 v41, 0, v65, s[20:21]
	v_fmac_f32_e32 v54, v46, v58
	v_fmac_f32_e32 v54, v28, v18
	v_mfma_f32_16x16x32_bf16 v[70:73], v[12:15], v[38:41], v[70:73]
	v_fmac_f32_e32 v55, v47, v58
	v_fmac_f32_e32 v55, v29, v18
	v_fmac_f32_e32 v55, v48, v59
	v_fmac_f32_e32 v55, v30, v19
	v_mfma_f32_16x16x32_bf16 v[74:77], v[8:11], v[38:41], v[74:77]
	v_fmac_f32_e32 v56, v49, v58
	v_fmac_f32_e32 v56, v31, v18
	v_fmac_f32_e32 v56, v22, v59
	v_fmac_f32_e32 v56, v32, v19
	v_fmac_f32_e32 v56, v23, v60
	v_fmac_f32_e32 v56, v33, v20
	v_mfma_f32_16x16x32_bf16 v[78:81], v[4:7], v[38:41], v[78:81]
	s_waitcnt lgkmcnt(12)
	v_fmac_f32_e32 v57, v24, v58
	v_fmac_f32_e32 v57, v34, v18
	v_fmac_f32_e32 v57, v25, v59
	v_fmac_f32_e32 v57, v35, v19
	v_mfma_f32_16x16x32_bf16 v[82:85], v[0:3], v[38:41], v[82:85]
	ds_read_b128 v[130:133], v118 offset:48
	ds_read_b128 v[106:109], v118 offset:64
	v_fmac_f32_e32 v57, v26, v60
	v_fmac_f32_e32 v57, v36, v20
	v_fmac_f32_e32 v57, v27, v61
	v_fmac_f32_e32 v57, v37, v21
	v_add_u32_e32 v0, 0x16800, v235
	ds_read_b128 v[110:113], v118 offset:80
	ds_read_b128 v[114:117], v118 offset:96
	ds_read_b128 v[118:121], v118 offset:112
	ds_write_b128 v0, v[54:57]
	v_cvt_pk_bf16_f32 v26, v70, v71
	v_cvt_pk_bf16_f32 v27, v72, v73
	v_cvt_pk_bf16_f32 v28, v74, v75
	v_cvt_pk_bf16_f32 v29, v76, v77
	v_cvt_pk_bf16_f32 v224, v78, v79
	v_cvt_pk_bf16_f32 v225, v80, v81
	s_waitcnt lgkmcnt(14)
	v_mfma_f32_16x16x32_bf16 v[30:33], v[236:239], v[26:29], 0
	v_cvt_pk_bf16_f32 v226, v82, v83
	v_cvt_pk_bf16_f32 v227, v84, v85
	s_and_b32 s24, s34, 6
	v_mfma_f32_16x16x32_bf16 v[236:239], v[244:247], v[26:29], 0
	v_lshl_add_u32 v0, s24, 9, v223
	s_lshl_b32 s25, s24, 10
	s_lshl_b32 s24, s24, 7
	v_mfma_f32_16x16x32_bf16 v[240:243], v[240:243], v[224:227], v[30:33]
	ds_read_b128 v[66:69], v0 offset:8192
	ds_read_b128 v[58:61], v0 offset:8256
	ds_read_b128 v[62:65], v0 offset:12288
	ds_read_b128 v[54:57], v0 offset:12352
	v_add_u32_e32 v0, s25, v231
	v_add_u32_e32 v18, s25, v232
	v_mfma_f32_16x16x32_bf16 v[224:227], v[248:251], v[224:227], v[236:239]
	s_add_i32 s24, s31, s24
	ds_read_b128 v[12:15], v0 offset:16384
	ds_read_b128 v[8:11], v0 offset:16640
	ds_read_b128 v[4:7], v0 offset:16896
	ds_read_b128 v[0:3], v0 offset:17152
	s_waitcnt lgkmcnt(14)
	v_fmac_f32_e32 v241, v134, v240
	v_fmac_f32_e32 v241, v124, v94
	v_fmac_f32_e32 v242, v135, v240
	v_fmac_f32_e32 v242, v125, v94
	v_fmac_f32_e32 v243, v137, v240
	v_fmac_f32_e32 v243, v127, v94
	v_fmac_f32_e32 v242, v136, v241
	v_fmac_f32_e32 v242, v126, v95
	v_fmac_f32_e32 v243, v122, v241
	v_fmac_f32_e32 v243, v128, v95
	v_fmac_f32_e32 v243, v123, v242
	v_fmac_f32_e32 v243, v129, v96
	v_cvt_pk_bf16_f32 v236, v240, v94
	v_cvt_pk_bf16_f32 v237, v241, v95
	v_cvt_pk_bf16_f32 v238, v242, v96
	v_cvt_pk_bf16_f32 v239, v243, v97
	s_waitcnt lgkmcnt(11)
	v_cndmask_b32_e64 v122, 0, v236, s[20:21]
	v_cndmask_b32_e64 v123, 0, v237, s[20:21]
	v_cndmask_b32_e64 v124, 0, v238, s[20:21]
	v_cndmask_b32_e64 v125, 0, v239, s[20:21]
	v_fmac_f32_e32 v224, v130, v240
	v_fmac_f32_e32 v224, v112, v94
	v_mfma_f32_16x16x32_bf16 v[70:73], v[102:105], v[122:125], v[70:73]
	s_waitcnt lgkmcnt(9)
	v_fmac_f32_e32 v225, v131, v240
	v_fmac_f32_e32 v225, v113, v94
	v_fmac_f32_e32 v225, v132, v241
	v_fmac_f32_e32 v225, v114, v95
	v_mfma_f32_16x16x32_bf16 v[74:77], v[98:101], v[122:125], v[74:77]
	v_fmac_f32_e32 v226, v133, v240
	v_fmac_f32_e32 v226, v115, v94
	v_fmac_f32_e32 v226, v106, v241
	v_fmac_f32_e32 v226, v116, v95
	v_fmac_f32_e32 v226, v107, v242
	v_fmac_f32_e32 v226, v117, v96
	v_mfma_f32_16x16x32_bf16 v[78:81], v[90:93], v[122:125], v[78:81]
	v_mov_b32_e32 v34, s24
	ds_read_b128 v[18:21], v18 offset:25600
	ds_read_b128 v[50:53], v34 offset:24576
	ds_read_b128 v[38:41], v34 offset:24592
	ds_read_b128 v[42:45], v34 offset:24608
	v_fmac_f32_e32 v227, v108, v240
	v_fmac_f32_e32 v227, v118, v94
	v_fmac_f32_e32 v227, v109, v241
	v_fmac_f32_e32 v227, v119, v95
	v_fmac_f32_e32 v227, v110, v242
	v_fmac_f32_e32 v227, v120, v96
	v_fmac_f32_e32 v227, v111, v243
	v_fmac_f32_e32 v227, v121, v97
	v_mfma_f32_16x16x32_bf16 v[82:85], v[86:89], v[122:125], v[82:85]
	ds_read_b128 v[46:49], v34 offset:24624
	ds_read_b128 v[22:25], v34 offset:24640
	ds_read_b128 v[26:29], v34 offset:24656
	ds_read_b128 v[30:33], v34 offset:24672
	ds_read_b128 v[34:37], v34 offset:24688
	s_cmp_lg_u32 s34, 8
	v_add_u32_e32 v86, 0x16c00, v235
	ds_write_b128 v86, v[224:227]
	s_cbranch_scc1 .LBB0_583
	v_add_u32_e32 v98, s31, v204
	ds_read_b128 v[86:89], v98 offset:7936
	ds_read_b128 v[90:93], v98 offset:8000
	ds_read_b128 v[94:97], v98 offset:8064
	ds_read_b128 v[98:101], v98 offset:8128
	s_waitcnt lgkmcnt(3)
	v_pk_mul_f32 v[72:73], v[72:73], v[88:89]
	v_pk_mul_f32 v[70:71], v[70:71], v[86:87]
	s_waitcnt lgkmcnt(2)
	v_pk_mul_f32 v[76:77], v[76:77], v[92:93]
	v_pk_mul_f32 v[74:75], v[74:75], v[90:91]
	s_waitcnt lgkmcnt(1)
	v_pk_mul_f32 v[80:81], v[80:81], v[96:97]
	v_pk_mul_f32 v[78:79], v[78:79], v[94:95]
	s_waitcnt lgkmcnt(0)
	v_pk_mul_f32 v[84:85], v[84:85], v[100:101]
	v_pk_mul_f32 v[82:83], v[82:83], v[98:99]

; #define MFMA(a, b, c) __builtin_amdgcn_mfma_f32_32x32x16_bf16((a), (b), (c), 0, 0, 0)
; __device__ __forceinline__ void at_partialSM(f32x16& p0, f32x16& p1, float& m_reg, float& alpha, bool force) {
;   float pm = p0[0];
; #pragma unroll
;   for (int r = 1; r < 16; ++r) pm = fmaxf(pm, p0[r]);
; #pragma unroll
;   for (int r = 0; r < 16; ++r) pm = fmaxf(pm, p1[r]);
;   { auto rr = __builtin_amdgcn_permlane32_swap(__float_as_uint(pm), __float_as_uint(pm), false, false);
;     pm = fmaxf(__uint_as_float(rr[0]), __uint_as_float(rr[1])); }
;   if (__builtin_expect(!force && __all(pm <= AT_THR * 1.4426950408889634f), 1)) { alpha = 1.f; }
;   else {
;     const float dlt = force ? pm : fmaxf(pm, 0.f);
;     alpha = force ? 1.f : __builtin_amdgcn_exp2f(-dlt); m_reg += dlt;
; #pragma unroll
;     for (int r = 0; r < 16; ++r) { p0[r] -= dlt; p1[r] -= dlt; }
;   }
; #pragma unroll
;   for (int r = 0; r < 16; ++r) p0[r] = __builtin_amdgcn_exp2f(p0[r]);
; }
; __device__ __forceinline__ void at_qkt(f32x16& p0, f32x16& p1, const char* Ks, const bf16x8* qr, int r32, int hi, float negm) {
; #pragma unroll
;   for (int r = 0; r < 16; ++r) { p0[r] = negm; p1[r] = negm; }
; #pragma unroll
;   for (int d0 = 0; d0 < 6; ++d0) {
;     const bf16x8 b0 = *(const bf16x8*)(Ks + r32 * AT_KROW + d0 * 32 + hi * 16);
;     const bf16x8 b1 = *(const bf16x8*)(Ks + (32 + r32) * AT_KROW + d0 * 32 + hi * 16);
;     p0 = MFMA(b0, qr[d0], p0);
;     p1 = MFMA(b1, qr[d0], p1);
;   }
; }
.Lat_nostag:
	ds_read_b128 v[200:203], v170 offset:64
	ds_read_b128 v[204:207], v170 offset:6720
	s_waitcnt lgkmcnt(4)
	v_mfma_f32_32x32x16_bf16 v[32:47], v[184:187], v[80:83], 0
	v_mfma_f32_32x32x16_bf16 v[48:63], v[188:191], v[80:83], 0
	ds_read_b128 v[208:211], v170 offset:96
	ds_read_b128 v[212:215], v170 offset:6752
	s_waitcnt lgkmcnt(4)
	v_mfma_f32_32x32x16_bf16 v[32:47], v[192:195], v[84:87], v[32:47]
	v_mfma_f32_32x32x16_bf16 v[48:63], v[196:199], v[84:87], v[48:63]
	ds_read_b128 v[184:187], v170 offset:128
	ds_read_b128 v[188:191], v170 offset:6784
	s_waitcnt lgkmcnt(4)
	v_mfma_f32_32x32x16_bf16 v[32:47], v[200:203], v[88:91], v[32:47]
	v_mfma_f32_32x32x16_bf16 v[48:63], v[204:207], v[88:91], v[48:63]
	ds_read_b128 v[192:195], v170 offset:160
	ds_read_b128 v[196:199], v170 offset:6816
	s_waitcnt lgkmcnt(4)
	v_mfma_f32_32x32x16_bf16 v[32:47], v[208:211], v[92:95], v[32:47]
	v_mfma_f32_32x32x16_bf16 v[48:63], v[212:215], v[92:95], v[48:63]
	s_waitcnt lgkmcnt(2)
	v_mfma_f32_32x32x16_bf16 v[32:47], v[184:187], v[96:99], v[32:47]
	v_mfma_f32_32x32x16_bf16 v[48:63], v[188:191], v[96:99], v[48:63]
	s_waitcnt lgkmcnt(0)
	v_mfma_f32_32x32x16_bf16 v[32:47], v[192:195], v[100:103], v[32:47]
	v_mfma_f32_32x32x16_bf16 v[48:63], v[196:199], v[100:103], v[48:63]
	s_nop 11
	v_max3_f32 v174, v32, v33, v34
	v_max3_f32 v175, v48, v49, v50
	v_max3_f32 v174, v174, v35, v36
	v_max3_f32 v175, v175, v51, v52
	v_max3_f32 v174, v174, v37, v38
	v_max3_f32 v175, v175, v53, v54
	v_max3_f32 v174, v174, v39, v40
	v_max3_f32 v175, v175, v55, v56
	v_max3_f32 v174, v174, v41, v42
	v_max3_f32 v175, v175, v57, v58
	v_max3_f32 v174, v174, v43, v44
	v_max3_f32 v175, v175, v59, v60
	v_max3_f32 v174, v174, v45, v46
	v_max3_f32 v175, v175, v61, v62
	v_max3_f32 v174, v174, v47, v63
	v_max_f32_e32 v174, v174, v175
	v_mov_b32_e32 v175, v174
	s_nop 1
	v_permlane32_swap_b32_e32 v174, v175
	v_max_f32_e32 v174, v174, v175
	s_barrier
	v_mov_b32_e32 v172, v174
	v_sub_f32_e32 v32, v32, v174
	v_sub_f32_e32 v48, v48, v174
	v_sub_f32_e32 v33, v33, v174
	v_sub_f32_e32 v49, v49, v174
	v_sub_f32_e32 v34, v34, v174
	v_sub_f32_e32 v50, v50, v174
	v_sub_f32_e32 v35, v35, v174
	v_sub_f32_e32 v51, v51, v174
	v_sub_f32_e32 v36, v36, v174
	v_sub_f32_e32 v52, v52, v174
	v_sub_f32_e32 v37, v37, v174
	v_sub_f32_e32 v53, v53, v174
	v_sub_f32_e32 v38, v38, v174
	v_sub_f32_e32 v54, v54, v174
	v_sub_f32_e32 v39, v39, v174
	v_sub_f32_e32 v55, v55, v174
	v_sub_f32_e32 v40, v40, v174
	v_sub_f32_e32 v56, v56, v174
	v_sub_f32_e32 v41, v41, v174
	v_sub_f32_e32 v57, v57, v174
	v_sub_f32_e32 v42, v42, v174
	v_sub_f32_e32 v58, v58, v174
	v_sub_f32_e32 v43, v43, v174
	v_sub_f32_e32 v59, v59, v174
	v_sub_f32_e32 v44, v44, v174
	v_sub_f32_e32 v60, v60, v174
	v_sub_f32_e32 v45, v45, v174
	v_sub_f32_e32 v61, v61, v174
	v_sub_f32_e32 v46, v46, v174
	v_sub_f32_e32 v62, v62, v174
	v_sub_f32_e32 v47, v47, v174
	v_sub_f32_e32 v63, v63, v174
	v_sub_f32_e32 v64, 0, v174
	v_sub_f32_e32 v65, 0, v174
	v_sub_f32_e32 v66, 0, v174
	v_sub_f32_e32 v67, 0, v174
	v_sub_f32_e32 v68, 0, v174
	v_sub_f32_e32 v69, 0, v174
	v_sub_f32_e32 v70, 0, v174
	v_sub_f32_e32 v71, 0, v174
	v_sub_f32_e32 v72, 0, v174
	v_sub_f32_e32 v73, 0, v174
	v_sub_f32_e32 v74, 0, v174
	v_sub_f32_e32 v75, 0, v174
	v_sub_f32_e32 v76, 0, v174
	v_sub_f32_e32 v77, 0, v174
	v_sub_f32_e32 v78, 0, v174
	v_sub_f32_e32 v79, 0, v174
	s_waitcnt vmcnt(0)
	ds_write_b128 v167, v[120:123] offset:26624
	ds_write_b128 v131, v[124:127] offset:32768
	ds_write_b128 v169, v[132:135] offset:26624
	v_exp_f32_e32 v32, v32
	v_exp_f32_e32 v48, v48
	v_exp_f32_e32 v33, v33
	v_exp_f32_e32 v49, v49
	v_exp_f32_e32 v34, v34
	v_exp_f32_e32 v50, v50
	v_exp_f32_e32 v35, v35
	v_exp_f32_e32 v51, v51
	v_exp_f32_e32 v36, v36
	v_exp_f32_e32 v52, v52
	v_exp_f32_e32 v37, v37
	v_exp_f32_e32 v53, v53
	v_exp_f32_e32 v38, v38
	v_exp_f32_e32 v54, v54
	v_exp_f32_e32 v39, v39
	v_exp_f32_e32 v55, v55
	v_exp_f32_e32 v40, v40
	v_exp_f32_e32 v56, v56
	v_exp_f32_e32 v41, v41
	v_exp_f32_e32 v57, v57
	v_exp_f32_e32 v42, v42
	v_exp_f32_e32 v58, v58
	v_exp_f32_e32 v43, v43
	v_exp_f32_e32 v59, v59
	v_exp_f32_e32 v44, v44
	v_exp_f32_e32 v60, v60
	v_exp_f32_e32 v45, v45
	v_exp_f32_e32 v61, v61
	v_exp_f32_e32 v46, v46
	v_exp_f32_e32 v62, v62
	v_exp_f32_e32 v47, v47
	v_exp_f32_e32 v63, v63
	s_waitcnt lgkmcnt(0)
	global_load_dwordx4 v[120:123], v129, s[4:5]
	global_load_dwordx4 v[124:127], v129, s[4:5] offset:128
	global_load_dwordx4 v[132:135], v130, s[6:7]
	s_add_u32 s4, s4, 0x40000
	s_addc_u32 s5, s5, 0
	s_add_u32 s6, s6, 0x1000
	s_addc_u32 s7, s7, 0
	v_add_f32_e32 v175, v32, v33
	v_add_f32_e32 v174, v48, v49
	v_add_f32_e32 v175, v175, v34
	v_add_f32_e32 v174, v174, v50
	v_add_f32_e32 v175, v175, v35
	v_add_f32_e32 v174, v174, v51
	v_add_f32_e32 v175, v175, v36
	v_add_f32_e32 v174, v174, v52
	v_add_f32_e32 v175, v175, v37
	v_add_f32_e32 v174, v174, v53
	v_add_f32_e32 v175, v175, v38
	v_add_f32_e32 v174, v174, v54
	v_add_f32_e32 v175, v175, v39
	v_add_f32_e32 v174, v174, v55
	v_add_f32_e32 v175, v175, v40
	v_add_f32_e32 v174, v174, v56
	v_add_f32_e32 v175, v175, v41
	v_add_f32_e32 v174, v174, v57
	v_add_f32_e32 v175, v175, v42
	v_add_f32_e32 v174, v174, v58
	v_add_f32_e32 v175, v175, v43
	v_add_f32_e32 v174, v174, v59
	v_add_f32_e32 v175, v175, v44
	v_add_f32_e32 v174, v174, v60
	v_add_f32_e32 v175, v175, v45
	v_add_f32_e32 v174, v174, v61
	v_add_f32_e32 v175, v175, v46
	v_add_f32_e32 v174, v174, v62
	v_add_f32_e32 v175, v175, v47
	v_add_f32_e32 v174, v174, v63
	v_add_f32_e32 v175, v175, v174
	v_add_f32_e32 v173, v173, v175
	v_cvt_pk_bf16_f32 v104, v32, v33
	v_cvt_pk_bf16_f32 v105, v34, v35
	v_cvt_pk_bf16_f32 v106, v36, v37
	v_cvt_pk_bf16_f32 v107, v38, v39
	v_cvt_pk_bf16_f32 v108, v40, v41
	v_cvt_pk_bf16_f32 v109, v42, v43
	v_cvt_pk_bf16_f32 v110, v44, v45
	v_cvt_pk_bf16_f32 v111, v46, v47
	v_cvt_pk_bf16_f32 v112, v48, v49
	v_cvt_pk_bf16_f32 v113, v50, v51
	v_cvt_pk_bf16_f32 v114, v52, v53
	v_cvt_pk_bf16_f32 v115, v54, v55
	v_cvt_pk_bf16_f32 v116, v56, v57
	v_cvt_pk_bf16_f32 v117, v58, v59
	v_cvt_pk_bf16_f32 v118, v60, v61
	v_cvt_pk_bf16_f32 v119, v62, v63
	ds_read_b128 v[184:187], v170 offset:13312
	ds_read_b128 v[188:191], v170 offset:19968
	ds_read_b128 v[192:195], v170 offset:13344
	ds_read_b128 v[196:199], v170 offset:20000
	s_barrier
	s_mov_b32 s13, 32
; #define MFMA(a, b, c) __builtin_amdgcn_mfma_f32_32x32x16_bf16((a), (b), (c), 0, 0, 0)
; #define SBAR() __builtin_amdgcn_sched_barrier(0)
; #define SLOAD(i, k0) do { sr_[i].vs = *(const bf16x8*)(Kh + (size_t)((k0) + skey) * 2048 + 64 + sc8); \
;     sr_[i].ks = *(const bf16x8*)(Kh + (size_t)((k0) + skey) * 2048 + sc8); \
;     sr_[i].ps = *(const bf16x8*)(Kp + (size_t)((k0) + pkey) * 32 + pc8); } while (0)
; #define SWRITE(bb, i) do { *(bf16x8*)(V_lds + (bb) * AT_SHMV + vst) = sr_[i].vs; \
;     *(bf16x8*)(K_lds + (bb) * AT_SHMK + kst) = sr_[i].ks; \
;     *(bf16x8*)(K_lds + (bb) * AT_SHMK + pst) = sr_[i].ps; } while (0)
; #define SWAIT() asm volatile("s_waitcnt vmcnt(3)" ::: "memory")
; #define RESC(a) do { if (__any((a) < 1.f)) { if (hi == 0) al_l[r32] = (a); asm volatile("s_waitcnt lgkmcnt(0)" ::: "memory"); \
;     _Pragma("unroll") for (int dd = 0; dd < 2; ++dd) _Pragma("unroll") for (int r = 0; r < 16; ++r) o[dd][r] *= al_l[crow(r, hi)]; } } while (0)
; __device__ __forceinline__ void at_qkt(f32x16& p0, f32x16& p1, const char* Ks, const bf16x8* qr, int r32, int hi, float negm) {
; #pragma unroll
;   for (int r = 0; r < 16; ++r) { p0[r] = negm; p1[r] = negm; }
; #pragma unroll
;   for (int d0 = 0; d0 < 6; ++d0) {
;     const bf16x8 b0 = *(const bf16x8*)(Ks + r32 * AT_KROW + d0 * 32 + hi * 16);
;     const bf16x8 b1 = *(const bf16x8*)(Ks + (32 + r32) * AT_KROW + d0 * 32 + hi * 16);
;     p0 = MFMA(b0, qr[d0], p0);
;     p1 = MFMA(b1, qr[d0], p1);
;   }
; }
; __device__ void phase_attn(const Params& p, char* lds) {
;     ...
;     for (int j = 1; j + 1 < NT; j += 2) {
;       SBAR(); at_qkt(pB0, pB1, K_lds + AT_SHMK, qr, r32, hi, -m_reg);
;       at_finishSM(pA0, pA1, alA, l_reg, pa0, pa1, pa2, pa3); SBAR();
;       SLOAD(1, (j + 2) * 64); SBAR();
;       pv_d0(o, vb0, pa0, pa1, pa2, pa3); at_partialSM(pB0, pB1, m_reg, alB, false);
;       __syncthreads(); SWAIT(); SWRITE(0, 0);
;       RESC(alB); __syncthreads();
;       SBAR(); at_qkt(pA0, pA1, K_lds, qr, r32, hi, -m_reg);
;       at_finishSM(pB0, pB1, alB, l_reg, pa0, pa1, pa2, pa3); SBAR();
;       if (j + 3 < NT) SLOAD(0, (j + 3) * 64); SBAR();
;       pv_d0(o, vb0 + AT_SHMV, pa0, pa1, pa2, pa3); at_partialSM(pA0, pA1, m_reg, alA, false);
;       __syncthreads(); SWAIT(); SWRITE(1, 1);
;       RESC(alA); __syncthreads();
.Lat_loop:
	ds_read_b128 v[200:203], v170 offset:13376
	ds_read_b128 v[204:207], v170 offset:20032
	s_waitcnt lgkmcnt(4)
	v_mfma_f32_32x32x16_bf16 v[32:47], v[184:187], v[80:83], v[64:79]
	v_mfma_f32_32x32x16_bf16 v[48:63], v[188:191], v[80:83], v[64:79]
	ds_read_b128 v[208:211], v170 offset:13408
	ds_read_b128 v[212:215], v170 offset:20064
	s_waitcnt lgkmcnt(4)
	v_mfma_f32_32x32x16_bf16 v[32:47], v[192:195], v[84:87], v[32:47]
	v_mfma_f32_32x32x16_bf16 v[48:63], v[196:199], v[84:87], v[48:63]
	ds_read_b128 v[184:187], v170 offset:13440
	ds_read_b128 v[188:191], v170 offset:20096
	s_waitcnt lgkmcnt(4)
	v_mfma_f32_32x32x16_bf16 v[32:47], v[200:203], v[88:91], v[32:47]
	v_mfma_f32_32x32x16_bf16 v[48:63], v[204:207], v[88:91], v[48:63]
	ds_read_b128 v[192:195], v170 offset:13472
	ds_read_b128 v[196:199], v170 offset:20128
	s_waitcnt lgkmcnt(4)
	v_mfma_f32_32x32x16_bf16 v[32:47], v[208:211], v[92:95], v[32:47]
	v_mfma_f32_32x32x16_bf16 v[48:63], v[212:215], v[92:95], v[48:63]
	ds_read_b64_tr_b16 v[148:149], v171 offset:0
	ds_read_b64_tr_b16 v[150:151], v171 offset:2048
	ds_read_b64_tr_b16 v[152:153], v171 offset:4096
	ds_read_b64_tr_b16 v[154:155], v171 offset:6144
	s_waitcnt lgkmcnt(6)
	v_mfma_f32_32x32x16_bf16 v[32:47], v[184:187], v[96:99], v[32:47]
	v_mfma_f32_32x32x16_bf16 v[48:63], v[188:191], v[96:99], v[48:63]
	ds_read_b64_tr_b16 v[156:157], v171 offset:8192
	ds_read_b64_tr_b16 v[158:159], v171 offset:10240
	ds_read_b64_tr_b16 v[216:217], v171 offset:12288
	ds_read_b64_tr_b16 v[218:219], v171 offset:14336
	s_waitcnt lgkmcnt(8)
	v_mfma_f32_32x32x16_bf16 v[32:47], v[192:195], v[100:103], v[32:47]
	v_mfma_f32_32x32x16_bf16 v[48:63], v[196:199], v[100:103], v[48:63]
	ds_read_b64_tr_b16 v[220:221], v171 offset:512
	ds_read_b64_tr_b16 v[222:223], v171 offset:2560
	ds_read_b64_tr_b16 v[224:225], v171 offset:4608
	ds_read_b64_tr_b16 v[226:227], v171 offset:6656
	s_waitcnt lgkmcnt(10)
	v_mfma_f32_32x32x16_bf16 v[0:15], v[104:107], v[148:151], v[0:15]
	s_waitcnt lgkmcnt(8)
	v_mfma_f32_32x32x16_bf16 v[0:15], v[108:111], v[152:155], v[0:15]
	ds_read_b64_tr_b16 v[236:237], v171 offset:8704
	ds_read_b64_tr_b16 v[238:239], v171 offset:10752
	ds_read_b64_tr_b16 v[240:241], v171 offset:12800
	ds_read_b64_tr_b16 v[242:243], v171 offset:14848
	s_waitcnt lgkmcnt(10)
	v_mfma_f32_32x32x16_bf16 v[0:15], v[112:115], v[156:159], v[0:15]
	s_waitcnt lgkmcnt(8)
	v_mfma_f32_32x32x16_bf16 v[0:15], v[116:119], v[216:219], v[0:15]
	s_waitcnt lgkmcnt(6)
	v_mfma_f32_32x32x16_bf16 v[16:31], v[104:107], v[220:223], v[16:31]
	s_waitcnt lgkmcnt(4)
	v_mfma_f32_32x32x16_bf16 v[16:31], v[108:111], v[224:227], v[16:31]
	s_waitcnt lgkmcnt(2)
	v_mfma_f32_32x32x16_bf16 v[16:31], v[112:115], v[236:239], v[16:31]
	s_waitcnt lgkmcnt(0)
	v_mfma_f32_32x32x16_bf16 v[16:31], v[116:119], v[240:243], v[16:31]
	s_barrier
	s_waitcnt vmcnt(0)
	ds_write_b128 v167, v[120:123] offset:39936
	ds_write_b128 v131, v[124:127] offset:49152
	ds_write_b128 v169, v[132:135] offset:39936
	v_exp_f32_e32 v32, v32
	v_exp_f32_e32 v48, v48
	v_exp_f32_e32 v33, v33
	v_exp_f32_e32 v49, v49
	v_exp_f32_e32 v34, v34
	v_exp_f32_e32 v50, v50
	v_exp_f32_e32 v35, v35
	v_exp_f32_e32 v51, v51
	v_exp_f32_e32 v36, v36
	v_exp_f32_e32 v52, v52
	v_exp_f32_e32 v37, v37
	v_exp_f32_e32 v53, v53
	v_exp_f32_e32 v38, v38
	v_exp_f32_e32 v54, v54
	v_exp_f32_e32 v39, v39
	v_exp_f32_e32 v55, v55
	v_exp_f32_e32 v40, v40
	v_exp_f32_e32 v56, v56
	v_exp_f32_e32 v41, v41
	v_exp_f32_e32 v57, v57
	v_exp_f32_e32 v42, v42
	v_exp_f32_e32 v58, v58
	v_exp_f32_e32 v43, v43
	v_exp_f32_e32 v59, v59
	v_exp_f32_e32 v44, v44
	v_exp_f32_e32 v60, v60
	v_exp_f32_e32 v45, v45
	v_exp_f32_e32 v61, v61
	v_exp_f32_e32 v46, v46
	v_exp_f32_e32 v62, v62
	v_exp_f32_e32 v47, v47
	v_exp_f32_e32 v63, v63
	s_waitcnt lgkmcnt(0)
	global_load_dwordx4 v[120:123], v129, s[4:5]
	global_load_dwordx4 v[124:127], v129, s[4:5] offset:128
	global_load_dwordx4 v[132:135], v130, s[6:7]
	s_add_u32 s4, s4, 0x40000
	s_addc_u32 s5, s5, 0
	s_add_u32 s6, s6, 0x1000
	s_addc_u32 s7, s7, 0
	v_add_f32_e32 v175, v32, v33
	v_add_f32_e32 v174, v48, v49
	v_add_f32_e32 v175, v175, v34
	v_add_f32_e32 v174, v174, v50
	v_add_f32_e32 v175, v175, v35
	v_add_f32_e32 v174, v174, v51
	v_add_f32_e32 v175, v175, v36
	v_add_f32_e32 v174, v174, v52
	v_add_f32_e32 v175, v175, v37
	v_add_f32_e32 v174, v174, v53
	v_add_f32_e32 v175, v175, v38
	v_add_f32_e32 v174, v174, v54
	v_add_f32_e32 v175, v175, v39
	v_add_f32_e32 v174, v174, v55
	v_add_f32_e32 v175, v175, v40
	v_add_f32_e32 v174, v174, v56
	v_add_f32_e32 v175, v175, v41
	v_add_f32_e32 v174, v174, v57
	v_add_f32_e32 v175, v175, v42
	v_add_f32_e32 v174, v174, v58
	v_add_f32_e32 v175, v175, v43
	v_add_f32_e32 v174, v174, v59
	v_add_f32_e32 v175, v175, v44
	v_add_f32_e32 v174, v174, v60
	v_add_f32_e32 v175, v175, v45
	v_add_f32_e32 v174, v174, v61
	v_add_f32_e32 v175, v175, v46
	v_add_f32_e32 v174, v174, v62
	v_add_f32_e32 v175, v175, v47
	v_add_f32_e32 v174, v174, v63
	v_add_f32_e32 v175, v175, v174
	v_cmp_ge_f32_e32 vcc, s23, v175
	s_cmp_eq_u64 vcc, exec
	s_cbranch_scc0 .Lat_rare0
; #define SBAR() __builtin_amdgcn_sched_barrier(0)
; #define SLOAD(i, k0) do { sr_[i].vs = *(const bf16x8*)(Kh + (size_t)((k0) + skey) * 2048 + 64 + sc8); \
;     sr_[i].ks = *(const bf16x8*)(Kh + (size_t)((k0) + skey) * 2048 + sc8); \
;     sr_[i].ps = *(const bf16x8*)(Kp + (size_t)((k0) + pkey) * 32 + pc8); } while (0)
; #define SWRITE(bb, i) do { *(bf16x8*)(V_lds + (bb) * AT_SHMV + vst) = sr_[i].vs; \
;     *(bf16x8*)(K_lds + (bb) * AT_SHMK + kst) = sr_[i].ks; \
;     *(bf16x8*)(K_lds + (bb) * AT_SHMK + pst) = sr_[i].ps; } while (0)
; #define SWAIT() asm volatile("s_waitcnt vmcnt(3)" ::: "memory")
; #define RESC(a) do { if (__any((a) < 1.f)) { if (hi == 0) al_l[r32] = (a); asm volatile("s_waitcnt lgkmcnt(0)" ::: "memory"); \
;     _Pragma("unroll") for (int dd = 0; dd < 2; ++dd) _Pragma("unroll") for (int r = 0; r < 16; ++r) o[dd][r] *= al_l[crow(r, hi)]; } } while (0)
; __device__ void phase_attn(const Params& p, char* lds) {
;     ...
;     for (int j = 1; j + 1 < NT; j += 2) {
;       SBAR(); at_qkt(pB0, pB1, K_lds + AT_SHMK, qr, r32, hi, -m_reg);
;       at_finishSM(pA0, pA1, alA, l_reg, pa0, pa1, pa2, pa3); SBAR();
;       SLOAD(1, (j + 2) * 64); SBAR();
;       pv_d0(o, vb0, pa0, pa1, pa2, pa3); at_partialSM(pB0, pB1, m_reg, alB, false);
;       __syncthreads(); SWAIT(); SWRITE(0, 0);
;       RESC(alB); __syncthreads();
;       SBAR(); at_qkt(pA0, pA1, K_lds, qr, r32, hi, -m_reg);
;       at_finishSM(pB0, pB1, alB, l_reg, pa0, pa1, pa2, pa3); SBAR();
;       if (j + 3 < NT) SLOAD(0, (j + 3) * 64); SBAR();
;       pv_d0(o, vb0 + AT_SHMV, pa0, pa1, pa2, pa3); at_partialSM(pA0, pA1, m_reg, alA, false);
;       __syncthreads(); SWAIT(); SWRITE(1, 1);
;       RESC(alA); __syncthreads();
.Lat_rare0_back:
	v_add_f32_e32 v173, v173, v175
	v_cvt_pk_bf16_f32 v104, v32, v33
	v_cvt_pk_bf16_f32 v105, v34, v35
	v_cvt_pk_bf16_f32 v106, v36, v37
	v_cvt_pk_bf16_f32 v107, v38, v39
	v_cvt_pk_bf16_f32 v108, v40, v41
	v_cvt_pk_bf16_f32 v109, v42, v43
	v_cvt_pk_bf16_f32 v110, v44, v45
	v_cvt_pk_bf16_f32 v111, v46, v47
	v_cvt_pk_bf16_f32 v112, v48, v49
	v_cvt_pk_bf16_f32 v113, v50, v51
	v_cvt_pk_bf16_f32 v114, v52, v53
	v_cvt_pk_bf16_f32 v115, v54, v55
	v_cvt_pk_bf16_f32 v116, v56, v57
	v_cvt_pk_bf16_f32 v117, v58, v59
	v_cvt_pk_bf16_f32 v118, v60, v61
	v_cvt_pk_bf16_f32 v119, v62, v63
	ds_read_b128 v[184:187], v170 offset:26624
	ds_read_b128 v[188:191], v170 offset:33280
	ds_read_b128 v[192:195], v170 offset:26656
	ds_read_b128 v[196:199], v170 offset:33312
	s_barrier
	ds_read_b128 v[200:203], v170 offset:26688
	ds_read_b128 v[204:207], v170 offset:33344
	s_waitcnt lgkmcnt(4)
	v_mfma_f32_32x32x16_bf16 v[32:47], v[184:187], v[80:83], v[64:79]
	v_mfma_f32_32x32x16_bf16 v[48:63], v[188:191], v[80:83], v[64:79]
	ds_read_b128 v[208:211], v170 offset:26720
	ds_read_b128 v[212:215], v170 offset:33376
	s_waitcnt lgkmcnt(4)
	v_mfma_f32_32x32x16_bf16 v[32:47], v[192:195], v[84:87], v[32:47]
	v_mfma_f32_32x32x16_bf16 v[48:63], v[196:199], v[84:87], v[48:63]
	ds_read_b128 v[184:187], v170 offset:26752
	ds_read_b128 v[188:191], v170 offset:33408
	s_waitcnt lgkmcnt(4)
	v_mfma_f32_32x32x16_bf16 v[32:47], v[200:203], v[88:91], v[32:47]
	v_mfma_f32_32x32x16_bf16 v[48:63], v[204:207], v[88:91], v[48:63]
	ds_read_b128 v[192:195], v170 offset:26784
	ds_read_b128 v[196:199], v170 offset:33440
	s_waitcnt lgkmcnt(4)
	v_mfma_f32_32x32x16_bf16 v[32:47], v[208:211], v[92:95], v[32:47]
	v_mfma_f32_32x32x16_bf16 v[48:63], v[212:215], v[92:95], v[48:63]
	ds_read_b64_tr_b16 v[148:149], v171 offset:16384
	ds_read_b64_tr_b16 v[150:151], v171 offset:18432
	ds_read_b64_tr_b16 v[152:153], v171 offset:20480
	ds_read_b64_tr_b16 v[154:155], v171 offset:22528
	s_waitcnt lgkmcnt(6)
	v_mfma_f32_32x32x16_bf16 v[32:47], v[184:187], v[96:99], v[32:47]
	v_mfma_f32_32x32x16_bf16 v[48:63], v[188:191], v[96:99], v[48:63]
	ds_read_b64_tr_b16 v[156:157], v171 offset:24576
	ds_read_b64_tr_b16 v[158:159], v171 offset:26624
	ds_read_b64_tr_b16 v[216:217], v171 offset:28672
	ds_read_b64_tr_b16 v[218:219], v171 offset:30720
	s_waitcnt lgkmcnt(8)
	v_mfma_f32_32x32x16_bf16 v[32:47], v[192:195], v[100:103], v[32:47]
	v_mfma_f32_32x32x16_bf16 v[48:63], v[196:199], v[100:103], v[48:63]
	ds_read_b64_tr_b16 v[220:221], v171 offset:16896
	ds_read_b64_tr_b16 v[222:223], v171 offset:18944
	ds_read_b64_tr_b16 v[224:225], v171 offset:20992
	ds_read_b64_tr_b16 v[226:227], v171 offset:23040
	s_waitcnt lgkmcnt(10)
	v_mfma_f32_32x32x16_bf16 v[0:15], v[104:107], v[148:151], v[0:15]
	s_waitcnt lgkmcnt(8)
	v_mfma_f32_32x32x16_bf16 v[0:15], v[108:111], v[152:155], v[0:15]
	ds_read_b64_tr_b16 v[236:237], v171 offset:25088
	ds_read_b64_tr_b16 v[238:239], v171 offset:27136
	ds_read_b64_tr_b16 v[240:241], v171 offset:29184
	ds_read_b64_tr_b16 v[242:243], v171 offset:31232
	s_waitcnt lgkmcnt(10)
	v_mfma_f32_32x32x16_bf16 v[0:15], v[112:115], v[156:159], v[0:15]
	s_waitcnt lgkmcnt(8)
	v_mfma_f32_32x32x16_bf16 v[0:15], v[116:119], v[216:219], v[0:15]
	s_waitcnt lgkmcnt(6)
	v_mfma_f32_32x32x16_bf16 v[16:31], v[104:107], v[220:223], v[16:31]
	s_waitcnt lgkmcnt(4)
	v_mfma_f32_32x32x16_bf16 v[16:31], v[108:111], v[224:227], v[16:31]
	s_waitcnt lgkmcnt(2)
	v_mfma_f32_32x32x16_bf16 v[16:31], v[112:115], v[236:239], v[16:31]
	s_waitcnt lgkmcnt(0)
	v_mfma_f32_32x32x16_bf16 v[16:31], v[116:119], v[240:243], v[16:31]
	s_barrier
	s_waitcnt vmcnt(0)
	ds_write_b128 v167, v[120:123] offset:0
	ds_write_b128 v131, v[124:127] offset:0
	ds_write_b128 v169, v[132:135] offset:0
	v_exp_f32_e32 v32, v32
	v_exp_f32_e32 v48, v48
	v_exp_f32_e32 v33, v33
	v_exp_f32_e32 v49, v49
	v_exp_f32_e32 v34, v34
	v_exp_f32_e32 v50, v50
	v_exp_f32_e32 v35, v35
	v_exp_f32_e32 v51, v51
	v_exp_f32_e32 v36, v36
	v_exp_f32_e32 v52, v52
	v_exp_f32_e32 v37, v37
	v_exp_f32_e32 v53, v53
	v_exp_f32_e32 v38, v38
	v_exp_f32_e32 v54, v54
	v_exp_f32_e32 v39, v39
	v_exp_f32_e32 v55, v55
	v_exp_f32_e32 v40, v40
	v_exp_f32_e32 v56, v56
	v_exp_f32_e32 v41, v41
	v_exp_f32_e32 v57, v57
	v_exp_f32_e32 v42, v42
	v_exp_f32_e32 v58, v58
	v_exp_f32_e32 v43, v43
	v_exp_f32_e32 v59, v59
	v_exp_f32_e32 v44, v44
	v_exp_f32_e32 v60, v60
	v_exp_f32_e32 v45, v45
	v_exp_f32_e32 v61, v61
	v_exp_f32_e32 v46, v46
	v_exp_f32_e32 v62, v62
	v_exp_f32_e32 v47, v47
	v_exp_f32_e32 v63, v63
	s_waitcnt lgkmcnt(0)
	global_load_dwordx4 v[120:123], v129, s[4:5]
	global_load_dwordx4 v[124:127], v129, s[4:5] offset:128
	global_load_dwordx4 v[132:135], v130, s[6:7]
	s_add_u32 s4, s4, 0x40000
	s_addc_u32 s5, s5, 0
	s_add_u32 s6, s6, 0x1000
	s_addc_u32 s7, s7, 0
	v_add_f32_e32 v175, v32, v33
	v_add_f32_e32 v174, v48, v49
	v_add_f32_e32 v175, v175, v34
	v_add_f32_e32 v174, v174, v50
	v_add_f32_e32 v175, v175, v35
	v_add_f32_e32 v174, v174, v51
	v_add_f32_e32 v175, v175, v36
	v_add_f32_e32 v174, v174, v52
	v_add_f32_e32 v175, v175, v37
	v_add_f32_e32 v174, v174, v53
	v_add_f32_e32 v175, v175, v38
	v_add_f32_e32 v174, v174, v54
	v_add_f32_e32 v175, v175, v39
	v_add_f32_e32 v174, v174, v55
	v_add_f32_e32 v175, v175, v40
	v_add_f32_e32 v174, v174, v56
	v_add_f32_e32 v175, v175, v41
	v_add_f32_e32 v174, v174, v57
	v_add_f32_e32 v175, v175, v42
	v_add_f32_e32 v174, v174, v58
	v_add_f32_e32 v175, v175, v43
	v_add_f32_e32 v174, v174, v59
	v_add_f32_e32 v175, v175, v44
	v_add_f32_e32 v174, v174, v60
	v_add_f32_e32 v175, v175, v45
	v_add_f32_e32 v174, v174, v61
	v_add_f32_e32 v175, v175, v46
	v_add_f32_e32 v174, v174, v62
	v_add_f32_e32 v175, v175, v47
	v_add_f32_e32 v174, v174, v63
	v_add_f32_e32 v175, v175, v174
	v_cmp_ge_f32_e32 vcc, s23, v175
	s_cmp_eq_u64 vcc, exec
	s_cbranch_scc0 .Lat_rare1
; #define SBAR() __builtin_amdgcn_sched_barrier(0)
; #define SLOAD(i, k0) do { sr_[i].vs = *(const bf16x8*)(Kh + (size_t)((k0) + skey) * 2048 + 64 + sc8); \
;     sr_[i].ks = *(const bf16x8*)(Kh + (size_t)((k0) + skey) * 2048 + sc8); \
;     sr_[i].ps = *(const bf16x8*)(Kp + (size_t)((k0) + pkey) * 32 + pc8); } while (0)
; #define SWRITE(bb, i) do { *(bf16x8*)(V_lds + (bb) * AT_SHMV + vst) = sr_[i].vs; \
;     *(bf16x8*)(K_lds + (bb) * AT_SHMK + kst) = sr_[i].ks; \
;     *(bf16x8*)(K_lds + (bb) * AT_SHMK + pst) = sr_[i].ps; } while (0)
; #define SWAIT() asm volatile("s_waitcnt vmcnt(3)" ::: "memory")
; #define RESC(a) do { if (__any((a) < 1.f)) { if (hi == 0) al_l[r32] = (a); asm volatile("s_waitcnt lgkmcnt(0)" ::: "memory"); \
;     _Pragma("unroll") for (int dd = 0; dd < 2; ++dd) _Pragma("unroll") for (int r = 0; r < 16; ++r) o[dd][r] *= al_l[crow(r, hi)]; } } while (0)
; __device__ void phase_attn(const Params& p, char* lds) {
;     ...
;     for (int j = 1; j + 1 < NT; j += 2) {
;       SBAR(); at_qkt(pB0, pB1, K_lds + AT_SHMK, qr, r32, hi, -m_reg);
;       at_finishSM(pA0, pA1, alA, l_reg, pa0, pa1, pa2, pa3); SBAR();
;       SLOAD(1, (j + 2) * 64); SBAR();
;       pv_d0(o, vb0, pa0, pa1, pa2, pa3); at_partialSM(pB0, pB1, m_reg, alB, false);
;       __syncthreads(); SWAIT(); SWRITE(0, 0);
;       RESC(alB); __syncthreads();
;       SBAR(); at_qkt(pA0, pA1, K_lds, qr, r32, hi, -m_reg);
;       at_finishSM(pB0, pB1, alB, l_reg, pa0, pa1, pa2, pa3); SBAR();
;       if (j + 3 < NT) SLOAD(0, (j + 3) * 64); SBAR();
;       pv_d0(o, vb0 + AT_SHMV, pa0, pa1, pa2, pa3); at_partialSM(pA0, pA1, m_reg, alA, false);
;       __syncthreads(); SWAIT(); SWRITE(1, 1);
;       RESC(alA); __syncthreads();
.Lat_rare1_back:
	v_add_f32_e32 v173, v173, v175
	v_cvt_pk_bf16_f32 v104, v32, v33
	v_cvt_pk_bf16_f32 v105, v34, v35
	v_cvt_pk_bf16_f32 v106, v36, v37
	v_cvt_pk_bf16_f32 v107, v38, v39
	v_cvt_pk_bf16_f32 v108, v40, v41
	v_cvt_pk_bf16_f32 v109, v42, v43
	v_cvt_pk_bf16_f32 v110, v44, v45
	v_cvt_pk_bf16_f32 v111, v46, v47
	v_cvt_pk_bf16_f32 v112, v48, v49
	v_cvt_pk_bf16_f32 v113, v50, v51
	v_cvt_pk_bf16_f32 v114, v52, v53
	v_cvt_pk_bf16_f32 v115, v54, v55
	v_cvt_pk_bf16_f32 v116, v56, v57
	v_cvt_pk_bf16_f32 v117, v58, v59
	v_cvt_pk_bf16_f32 v118, v60, v61
	v_cvt_pk_bf16_f32 v119, v62, v63
	ds_read_b128 v[184:187], v170 offset:39936
	ds_read_b128 v[188:191], v170 offset:46592
	ds_read_b128 v[192:195], v170 offset:39968
	ds_read_b128 v[196:199], v170 offset:46624
	s_barrier
	ds_read_b128 v[200:203], v170 offset:40000
	ds_read_b128 v[204:207], v170 offset:46656
	s_waitcnt lgkmcnt(4)
	v_mfma_f32_32x32x16_bf16 v[32:47], v[184:187], v[80:83], v[64:79]
	v_mfma_f32_32x32x16_bf16 v[48:63], v[188:191], v[80:83], v[64:79]
	ds_read_b128 v[208:211], v170 offset:40032
	ds_read_b128 v[212:215], v170 offset:46688
	s_waitcnt lgkmcnt(4)
	v_mfma_f32_32x32x16_bf16 v[32:47], v[192:195], v[84:87], v[32:47]
	v_mfma_f32_32x32x16_bf16 v[48:63], v[196:199], v[84:87], v[48:63]
	ds_read_b128 v[184:187], v170 offset:40064
	ds_read_b128 v[188:191], v170 offset:46720
	s_waitcnt lgkmcnt(4)
	v_mfma_f32_32x32x16_bf16 v[32:47], v[200:203], v[88:91], v[32:47]
	v_mfma_f32_32x32x16_bf16 v[48:63], v[204:207], v[88:91], v[48:63]
	ds_read_b128 v[192:195], v170 offset:40096
	ds_read_b128 v[196:199], v170 offset:46752
	s_waitcnt lgkmcnt(4)
	v_mfma_f32_32x32x16_bf16 v[32:47], v[208:211], v[92:95], v[32:47]
	v_mfma_f32_32x32x16_bf16 v[48:63], v[212:215], v[92:95], v[48:63]
	ds_read_b64_tr_b16 v[148:149], v171 offset:32768
	ds_read_b64_tr_b16 v[150:151], v171 offset:34816
	ds_read_b64_tr_b16 v[152:153], v171 offset:36864
	ds_read_b64_tr_b16 v[154:155], v171 offset:38912
	s_waitcnt lgkmcnt(6)
	v_mfma_f32_32x32x16_bf16 v[32:47], v[184:187], v[96:99], v[32:47]
	v_mfma_f32_32x32x16_bf16 v[48:63], v[188:191], v[96:99], v[48:63]
	ds_read_b64_tr_b16 v[156:157], v171 offset:40960
	ds_read_b64_tr_b16 v[158:159], v171 offset:43008
	ds_read_b64_tr_b16 v[216:217], v171 offset:45056
	ds_read_b64_tr_b16 v[218:219], v171 offset:47104
	s_waitcnt lgkmcnt(8)
	v_mfma_f32_32x32x16_bf16 v[32:47], v[192:195], v[100:103], v[32:47]
	v_mfma_f32_32x32x16_bf16 v[48:63], v[196:199], v[100:103], v[48:63]
	ds_read_b64_tr_b16 v[220:221], v171 offset:33280
	ds_read_b64_tr_b16 v[222:223], v171 offset:35328
	ds_read_b64_tr_b16 v[224:225], v171 offset:37376
	ds_read_b64_tr_b16 v[226:227], v171 offset:39424
	s_waitcnt lgkmcnt(10)
	v_mfma_f32_32x32x16_bf16 v[0:15], v[104:107], v[148:151], v[0:15]
	s_waitcnt lgkmcnt(8)
	v_mfma_f32_32x32x16_bf16 v[0:15], v[108:111], v[152:155], v[0:15]
	ds_read_b64_tr_b16 v[236:237], v171 offset:41472
	ds_read_b64_tr_b16 v[238:239], v171 offset:43520
	ds_read_b64_tr_b16 v[240:241], v171 offset:45568
	ds_read_b64_tr_b16 v[242:243], v171 offset:47616
	s_waitcnt lgkmcnt(10)
	v_mfma_f32_32x32x16_bf16 v[0:15], v[112:115], v[156:159], v[0:15]
	s_waitcnt lgkmcnt(8)
	v_mfma_f32_32x32x16_bf16 v[0:15], v[116:119], v[216:219], v[0:15]
	s_waitcnt lgkmcnt(6)
	v_mfma_f32_32x32x16_bf16 v[16:31], v[104:107], v[220:223], v[16:31]
	s_waitcnt lgkmcnt(4)
	v_mfma_f32_32x32x16_bf16 v[16:31], v[108:111], v[224:227], v[16:31]
	s_waitcnt lgkmcnt(2)
	v_mfma_f32_32x32x16_bf16 v[16:31], v[112:115], v[236:239], v[16:31]
	s_waitcnt lgkmcnt(0)
	v_mfma_f32_32x32x16_bf16 v[16:31], v[116:119], v[240:243], v[16:31]
	s_barrier
	s_waitcnt vmcnt(0)
	ds_write_b128 v167, v[120:123] offset:13312
	ds_write_b128 v131, v[124:127] offset:16384
	ds_write_b128 v169, v[132:135] offset:13312
	v_exp_f32_e32 v32, v32
	v_exp_f32_e32 v48, v48
	v_exp_f32_e32 v33, v33
	v_exp_f32_e32 v49, v49
	v_exp_f32_e32 v34, v34
	v_exp_f32_e32 v50, v50
	v_exp_f32_e32 v35, v35
	v_exp_f32_e32 v51, v51
	v_exp_f32_e32 v36, v36
	v_exp_f32_e32 v52, v52
	v_exp_f32_e32 v37, v37
	v_exp_f32_e32 v53, v53
	v_exp_f32_e32 v38, v38
	v_exp_f32_e32 v54, v54
	v_exp_f32_e32 v39, v39
	v_exp_f32_e32 v55, v55
	v_exp_f32_e32 v40, v40
	v_exp_f32_e32 v56, v56
	v_exp_f32_e32 v41, v41
	v_exp_f32_e32 v57, v57
	v_exp_f32_e32 v42, v42
	v_exp_f32_e32 v58, v58
	v_exp_f32_e32 v43, v43
	v_exp_f32_e32 v59, v59
	v_exp_f32_e32 v44, v44
	v_exp_f32_e32 v60, v60
	v_exp_f32_e32 v45, v45
	v_exp_f32_e32 v61, v61
	v_exp_f32_e32 v46, v46
	v_exp_f32_e32 v62, v62
	v_exp_f32_e32 v47, v47
	v_exp_f32_e32 v63, v63
	s_waitcnt lgkmcnt(0)
	global_load_dwordx4 v[120:123], v129, s[4:5]
	global_load_dwordx4 v[124:127], v129, s[4:5] offset:128
	global_load_dwordx4 v[132:135], v130, s[6:7]
	s_add_u32 s4, s4, 0x40000
	s_addc_u32 s5, s5, 0
	s_add_u32 s6, s6, 0x1000
	s_addc_u32 s7, s7, 0
	v_add_f32_e32 v175, v32, v33
	v_add_f32_e32 v174, v48, v49
	v_add_f32_e32 v175, v175, v34
	v_add_f32_e32 v174, v174, v50
	v_add_f32_e32 v175, v175, v35
	v_add_f32_e32 v174, v174, v51
	v_add_f32_e32 v175, v175, v36
	v_add_f32_e32 v174, v174, v52
	v_add_f32_e32 v175, v175, v37
	v_add_f32_e32 v174, v174, v53
	v_add_f32_e32 v175, v175, v38
	v_add_f32_e32 v174, v174, v54
	v_add_f32_e32 v175, v175, v39
	v_add_f32_e32 v174, v174, v55
	v_add_f32_e32 v175, v175, v40
	v_add_f32_e32 v174, v174, v56
	v_add_f32_e32 v175, v175, v41
	v_add_f32_e32 v174, v174, v57
	v_add_f32_e32 v175, v175, v42
	v_add_f32_e32 v174, v174, v58
	v_add_f32_e32 v175, v175, v43
	v_add_f32_e32 v174, v174, v59
	v_add_f32_e32 v175, v175, v44
	v_add_f32_e32 v174, v174, v60
	v_add_f32_e32 v175, v175, v45
	v_add_f32_e32 v174, v174, v61
	v_add_f32_e32 v175, v175, v46
	v_add_f32_e32 v174, v174, v62
	v_add_f32_e32 v175, v175, v47
	v_add_f32_e32 v174, v174, v63
	v_add_f32_e32 v175, v175, v174
	v_cmp_ge_f32_e32 vcc, s23, v175
	s_cmp_eq_u64 vcc, exec
	s_cbranch_scc0 .Lat_rare2
; #define SBAR() __builtin_amdgcn_sched_barrier(0)
; #define SLOAD(i, k0) do { sr_[i].vs = *(const bf16x8*)(Kh + (size_t)((k0) + skey) * 2048 + 64 + sc8); \
;     sr_[i].ks = *(const bf16x8*)(Kh + (size_t)((k0) + skey) * 2048 + sc8); \
;     sr_[i].ps = *(const bf16x8*)(Kp + (size_t)((k0) + pkey) * 32 + pc8); } while (0)
; #define SWRITE(bb, i) do { *(bf16x8*)(V_lds + (bb) * AT_SHMV + vst) = sr_[i].vs; \
;     *(bf16x8*)(K_lds + (bb) * AT_SHMK + kst) = sr_[i].ks; \
;     *(bf16x8*)(K_lds + (bb) * AT_SHMK + pst) = sr_[i].ps; } while (0)
; #define SWAIT() asm volatile("s_waitcnt vmcnt(3)" ::: "memory")
; #define RESC(a) do { if (__any((a) < 1.f)) { if (hi == 0) al_l[r32] = (a); asm volatile("s_waitcnt lgkmcnt(0)" ::: "memory"); \
;     _Pragma("unroll") for (int dd = 0; dd < 2; ++dd) _Pragma("unroll") for (int r = 0; r < 16; ++r) o[dd][r] *= al_l[crow(r, hi)]; } } while (0)
; __device__ void phase_attn(const Params& p, char* lds) {
;     ...
;     for (int j = 1; j + 1 < NT; j += 2) {
;       SBAR(); at_qkt(pB0, pB1, K_lds + AT_SHMK, qr, r32, hi, -m_reg);
;       at_finishSM(pA0, pA1, alA, l_reg, pa0, pa1, pa2, pa3); SBAR();
;       SLOAD(1, (j + 2) * 64); SBAR();
;       pv_d0(o, vb0, pa0, pa1, pa2, pa3); at_partialSM(pB0, pB1, m_reg, alB, false);
;       __syncthreads(); SWAIT(); SWRITE(0, 0);
;       RESC(alB); __syncthreads();
;       SBAR(); at_qkt(pA0, pA1, K_lds, qr, r32, hi, -m_reg);
;       at_finishSM(pB0, pB1, alB, l_reg, pa0, pa1, pa2, pa3); SBAR();
;       if (j + 3 < NT) SLOAD(0, (j + 3) * 64); SBAR();
;       pv_d0(o, vb0 + AT_SHMV, pa0, pa1, pa2, pa3); at_partialSM(pA0, pA1, m_reg, alA, false);
;       __syncthreads(); SWAIT(); SWRITE(1, 1);
;       RESC(alA); __syncthreads();
.Lat_rare2_back:
	v_add_f32_e32 v173, v173, v175
	v_cvt_pk_bf16_f32 v104, v32, v33
	v_cvt_pk_bf16_f32 v105, v34, v35
	v_cvt_pk_bf16_f32 v106, v36, v37
	v_cvt_pk_bf16_f32 v107, v38, v39
	v_cvt_pk_bf16_f32 v108, v40, v41
	v_cvt_pk_bf16_f32 v109, v42, v43
	v_cvt_pk_bf16_f32 v110, v44, v45
	v_cvt_pk_bf16_f32 v111, v46, v47
	v_cvt_pk_bf16_f32 v112, v48, v49
	v_cvt_pk_bf16_f32 v113, v50, v51
	v_cvt_pk_bf16_f32 v114, v52, v53
	v_cvt_pk_bf16_f32 v115, v54, v55
	v_cvt_pk_bf16_f32 v116, v56, v57
	v_cvt_pk_bf16_f32 v117, v58, v59
	v_cvt_pk_bf16_f32 v118, v60, v61
	v_cvt_pk_bf16_f32 v119, v62, v63
	ds_read_b128 v[184:187], v170 offset:0
	ds_read_b128 v[188:191], v170 offset:6656
	ds_read_b128 v[192:195], v170 offset:32
	ds_read_b128 v[196:199], v170 offset:6688
	s_barrier
	ds_read_b128 v[200:203], v170 offset:64
	ds_read_b128 v[204:207], v170 offset:6720
	s_waitcnt lgkmcnt(4)
	v_mfma_f32_32x32x16_bf16 v[32:47], v[184:187], v[80:83], v[64:79]
	v_mfma_f32_32x32x16_bf16 v[48:63], v[188:191], v[80:83], v[64:79]
	ds_read_b128 v[208:211], v170 offset:96
	ds_read_b128 v[212:215], v170 offset:6752
	s_waitcnt lgkmcnt(4)
	v_mfma_f32_32x32x16_bf16 v[32:47], v[192:195], v[84:87], v[32:47]
	v_mfma_f32_32x32x16_bf16 v[48:63], v[196:199], v[84:87], v[48:63]
	ds_read_b128 v[184:187], v170 offset:128
	ds_read_b128 v[188:191], v170 offset:6784
	s_waitcnt lgkmcnt(4)
	v_mfma_f32_32x32x16_bf16 v[32:47], v[200:203], v[88:91], v[32:47]
	v_mfma_f32_32x32x16_bf16 v[48:63], v[204:207], v[88:91], v[48:63]
	ds_read_b128 v[192:195], v170 offset:160
	ds_read_b128 v[196:199], v170 offset:6816
	s_waitcnt lgkmcnt(4)
	v_mfma_f32_32x32x16_bf16 v[32:47], v[208:211], v[92:95], v[32:47]
	v_mfma_f32_32x32x16_bf16 v[48:63], v[212:215], v[92:95], v[48:63]
	ds_read_b64_tr_b16 v[148:149], v171 offset:49152
	ds_read_b64_tr_b16 v[150:151], v171 offset:51200
	ds_read_b64_tr_b16 v[152:153], v171 offset:53248
	ds_read_b64_tr_b16 v[154:155], v171 offset:55296
	s_waitcnt lgkmcnt(6)
	v_mfma_f32_32x32x16_bf16 v[32:47], v[184:187], v[96:99], v[32:47]
	v_mfma_f32_32x32x16_bf16 v[48:63], v[188:191], v[96:99], v[48:63]
	ds_read_b64_tr_b16 v[156:157], v171 offset:57344
	ds_read_b64_tr_b16 v[158:159], v171 offset:59392
	ds_read_b64_tr_b16 v[216:217], v171 offset:61440
	ds_read_b64_tr_b16 v[218:219], v171 offset:63488
	s_waitcnt lgkmcnt(8)
	v_mfma_f32_32x32x16_bf16 v[32:47], v[192:195], v[100:103], v[32:47]
	v_mfma_f32_32x32x16_bf16 v[48:63], v[196:199], v[100:103], v[48:63]
	ds_read_b64_tr_b16 v[220:221], v171 offset:49664
	ds_read_b64_tr_b16 v[222:223], v171 offset:51712
	ds_read_b64_tr_b16 v[224:225], v171 offset:53760
	ds_read_b64_tr_b16 v[226:227], v171 offset:55808
	s_waitcnt lgkmcnt(10)
	v_mfma_f32_32x32x16_bf16 v[0:15], v[104:107], v[148:151], v[0:15]
	s_waitcnt lgkmcnt(8)
	v_mfma_f32_32x32x16_bf16 v[0:15], v[108:111], v[152:155], v[0:15]
	ds_read_b64_tr_b16 v[236:237], v171 offset:57856
	ds_read_b64_tr_b16 v[238:239], v171 offset:59904
	ds_read_b64_tr_b16 v[240:241], v171 offset:61952
	ds_read_b64_tr_b16 v[242:243], v171 offset:64000
	s_waitcnt lgkmcnt(10)
	v_mfma_f32_32x32x16_bf16 v[0:15], v[112:115], v[156:159], v[0:15]
	s_waitcnt lgkmcnt(8)
	v_mfma_f32_32x32x16_bf16 v[0:15], v[116:119], v[216:219], v[0:15]
	s_waitcnt lgkmcnt(6)
	v_mfma_f32_32x32x16_bf16 v[16:31], v[104:107], v[220:223], v[16:31]
	s_waitcnt lgkmcnt(4)
	v_mfma_f32_32x32x16_bf16 v[16:31], v[108:111], v[224:227], v[16:31]
	s_waitcnt lgkmcnt(2)
	v_mfma_f32_32x32x16_bf16 v[16:31], v[112:115], v[236:239], v[16:31]
	s_waitcnt lgkmcnt(0)
	v_mfma_f32_32x32x16_bf16 v[16:31], v[116:119], v[240:243], v[16:31]
	s_barrier
	s_waitcnt vmcnt(0)
	ds_write_b128 v167, v[120:123] offset:26624
	ds_write_b128 v131, v[124:127] offset:32768
	ds_write_b128 v169, v[132:135] offset:26624
	v_exp_f32_e32 v32, v32
	v_exp_f32_e32 v48, v48
	v_exp_f32_e32 v33, v33
	v_exp_f32_e32 v49, v49
	v_exp_f32_e32 v34, v34
	v_exp_f32_e32 v50, v50
	v_exp_f32_e32 v35, v35
	v_exp_f32_e32 v51, v51
	v_exp_f32_e32 v36, v36
	v_exp_f32_e32 v52, v52
	v_exp_f32_e32 v37, v37
	v_exp_f32_e32 v53, v53
	v_exp_f32_e32 v38, v38
	v_exp_f32_e32 v54, v54
	v_exp_f32_e32 v39, v39
	v_exp_f32_e32 v55, v55
	v_exp_f32_e32 v40, v40
	v_exp_f32_e32 v56, v56
	v_exp_f32_e32 v41, v41
	v_exp_f32_e32 v57, v57
	v_exp_f32_e32 v42, v42
	v_exp_f32_e32 v58, v58
	v_exp_f32_e32 v43, v43
	v_exp_f32_e32 v59, v59
	v_exp_f32_e32 v44, v44
	v_exp_f32_e32 v60, v60
	v_exp_f32_e32 v45, v45
	v_exp_f32_e32 v61, v61
	v_exp_f32_e32 v46, v46
	v_exp_f32_e32 v62, v62
	v_exp_f32_e32 v47, v47
	v_exp_f32_e32 v63, v63
	s_waitcnt lgkmcnt(0)
	global_load_dwordx4 v[120:123], v129, s[4:5]
	global_load_dwordx4 v[124:127], v129, s[4:5] offset:128
	global_load_dwordx4 v[132:135], v130, s[6:7]
	s_add_u32 s4, s4, 0x40000
	s_addc_u32 s5, s5, 0
	s_add_u32 s6, s6, 0x1000
	s_addc_u32 s7, s7, 0
	v_add_f32_e32 v175, v32, v33
	v_add_f32_e32 v174, v48, v49
	v_add_f32_e32 v175, v175, v34
	v_add_f32_e32 v174, v174, v50
	v_add_f32_e32 v175, v175, v35
	v_add_f32_e32 v174, v174, v51
	v_add_f32_e32 v175, v175, v36
	v_add_f32_e32 v174, v174, v52
	v_add_f32_e32 v175, v175, v37
	v_add_f32_e32 v174, v174, v53
	v_add_f32_e32 v175, v175, v38
	v_add_f32_e32 v174, v174, v54
	v_add_f32_e32 v175, v175, v39
	v_add_f32_e32 v174, v174, v55
	v_add_f32_e32 v175, v175, v40
	v_add_f32_e32 v174, v174, v56
	v_add_f32_e32 v175, v175, v41
	v_add_f32_e32 v174, v174, v57
	v_add_f32_e32 v175, v175, v42
	v_add_f32_e32 v174, v174, v58
	v_add_f32_e32 v175, v175, v43
	v_add_f32_e32 v174, v174, v59
	v_add_f32_e32 v175, v175, v44
	v_add_f32_e32 v174, v174, v60
	v_add_f32_e32 v175, v175, v45
	v_add_f32_e32 v174, v174, v61
	v_add_f32_e32 v175, v175, v46
	v_add_f32_e32 v174, v174, v62
	v_add_f32_e32 v175, v175, v47
	v_add_f32_e32 v174, v174, v63
	v_add_f32_e32 v175, v175, v174
	v_cmp_ge_f32_e32 vcc, s23, v175
	s_cmp_eq_u64 vcc, exec
	s_cbranch_scc0 .Lat_rare3
; #define SBAR() __builtin_amdgcn_sched_barrier(0)
; #define SLOAD(i, k0) do { sr_[i].vs = *(const bf16x8*)(Kh + (size_t)((k0) + skey) * 2048 + 64 + sc8); \
;     sr_[i].ks = *(const bf16x8*)(Kh + (size_t)((k0) + skey) * 2048 + sc8); \
;     sr_[i].ps = *(const bf16x8*)(Kp + (size_t)((k0) + pkey) * 32 + pc8); } while (0)
; #define SWRITE(bb, i) do { *(bf16x8*)(V_lds + (bb) * AT_SHMV + vst) = sr_[i].vs; \
;     *(bf16x8*)(K_lds + (bb) * AT_SHMK + kst) = sr_[i].ks; \
;     *(bf16x8*)(K_lds + (bb) * AT_SHMK + pst) = sr_[i].ps; } while (0)
; #define SWAIT() asm volatile("s_waitcnt vmcnt(3)" ::: "memory")
; #define RESC(a) do { if (__any((a) < 1.f)) { if (hi == 0) al_l[r32] = (a); asm volatile("s_waitcnt lgkmcnt(0)" ::: "memory"); \
;     _Pragma("unroll") for (int dd = 0; dd < 2; ++dd) _Pragma("unroll") for (int r = 0; r < 16; ++r) o[dd][r] *= al_l[crow(r, hi)]; } } while (0)
; __device__ void phase_attn(const Params& p, char* lds) {
;     ...
;     for (int j = 1; j + 1 < NT; j += 2) {
;       SBAR(); at_qkt(pB0, pB1, K_lds + AT_SHMK, qr, r32, hi, -m_reg);
;       at_finishSM(pA0, pA1, alA, l_reg, pa0, pa1, pa2, pa3); SBAR();
;       SLOAD(1, (j + 2) * 64); SBAR();
;       pv_d0(o, vb0, pa0, pa1, pa2, pa3); at_partialSM(pB0, pB1, m_reg, alB, false);
;       __syncthreads(); SWAIT(); SWRITE(0, 0);
;       RESC(alB); __syncthreads();
;       SBAR(); at_qkt(pA0, pA1, K_lds, qr, r32, hi, -m_reg);
;       at_finishSM(pB0, pB1, alB, l_reg, pa0, pa1, pa2, pa3); SBAR();
;       if (j + 3 < NT) SLOAD(0, (j + 3) * 64); SBAR();
;       pv_d0(o, vb0 + AT_SHMV, pa0, pa1, pa2, pa3); at_partialSM(pA0, pA1, m_reg, alA, false);
;       __syncthreads(); SWAIT(); SWRITE(1, 1);
;       RESC(alA); __syncthreads();
;     }
;     SBAR(); at_qkt(pB0, pB1, K_lds + AT_SHMK, qr, r32, hi, -m_reg);
;     at_finishSM(pA0, pA1, alA, l_reg, pa0, pa1, pa2, pa3); SBAR();
.Lat_rare3_back:
	v_add_f32_e32 v173, v173, v175
	v_cvt_pk_bf16_f32 v104, v32, v33
	v_cvt_pk_bf16_f32 v105, v34, v35
	v_cvt_pk_bf16_f32 v106, v36, v37
	v_cvt_pk_bf16_f32 v107, v38, v39
	v_cvt_pk_bf16_f32 v108, v40, v41
	v_cvt_pk_bf16_f32 v109, v42, v43
	v_cvt_pk_bf16_f32 v110, v44, v45
	v_cvt_pk_bf16_f32 v111, v46, v47
	v_cvt_pk_bf16_f32 v112, v48, v49
	v_cvt_pk_bf16_f32 v113, v50, v51
	v_cvt_pk_bf16_f32 v114, v52, v53
	v_cvt_pk_bf16_f32 v115, v54, v55
	v_cvt_pk_bf16_f32 v116, v56, v57
	v_cvt_pk_bf16_f32 v117, v58, v59
	v_cvt_pk_bf16_f32 v118, v60, v61
	v_cvt_pk_bf16_f32 v119, v62, v63
	ds_read_b128 v[184:187], v170 offset:13312
	ds_read_b128 v[188:191], v170 offset:19968
	ds_read_b128 v[192:195], v170 offset:13344
	ds_read_b128 v[196:199], v170 offset:20000
	s_barrier
	s_sub_u32 s13, s13, 1
	s_cmp_lg_u32 s13, 0
	s_cbranch_scc1 .Lat_loop
	ds_read_b128 v[200:203], v170 offset:13376
	ds_read_b128 v[204:207], v170 offset:20032
	s_waitcnt lgkmcnt(4)
	v_mfma_f32_32x32x16_bf16 v[32:47], v[184:187], v[80:83], v[64:79]
	v_mfma_f32_32x32x16_bf16 v[48:63], v[188:191], v[80:83], v[64:79]
	ds_read_b128 v[208:211], v170 offset:13408
	ds_read_b128 v[212:215], v170 offset:20064
	s_waitcnt lgkmcnt(4)
	v_mfma_f32_32x32x16_bf16 v[32:47], v[192:195], v[84:87], v[32:47]
	v_mfma_f32_32x32x16_bf16 v[48:63], v[196:199], v[84:87], v[48:63]
	ds_read_b128 v[184:187], v170 offset:13440
	ds_read_b128 v[188:191], v170 offset:20096
	s_waitcnt lgkmcnt(4)
	v_mfma_f32_32x32x16_bf16 v[32:47], v[200:203], v[88:91], v[32:47]
	v_mfma_f32_32x32x16_bf16 v[48:63], v[204:207], v[88:91], v[48:63]
	ds_read_b128 v[192:195], v170 offset:13472
	ds_read_b128 v[196:199], v170 offset:20128
	s_waitcnt lgkmcnt(4)
	v_mfma_f32_32x32x16_bf16 v[32:47], v[208:211], v[92:95], v[32:47]
	v_mfma_f32_32x32x16_bf16 v[48:63], v[212:215], v[92:95], v[48:63]
	ds_read_b64_tr_b16 v[148:149], v171 offset:0
	ds_read_b64_tr_b16 v[150:151], v171 offset:2048
	ds_read_b64_tr_b16 v[152:153], v171 offset:4096
	ds_read_b64_tr_b16 v[154:155], v171 offset:6144
	s_waitcnt lgkmcnt(6)
	v_mfma_f32_32x32x16_bf16 v[32:47], v[184:187], v[96:99], v[32:47]
	v_mfma_f32_32x32x16_bf16 v[48:63], v[188:191], v[96:99], v[48:63]
	ds_read_b64_tr_b16 v[156:157], v171 offset:8192
	ds_read_b64_tr_b16 v[158:159], v171 offset:10240
	ds_read_b64_tr_b16 v[216:217], v171 offset:12288
	ds_read_b64_tr_b16 v[218:219], v171 offset:14336
	s_waitcnt lgkmcnt(8)
	v_mfma_f32_32x32x16_bf16 v[32:47], v[192:195], v[100:103], v[32:47]
	v_mfma_f32_32x32x16_bf16 v[48:63], v[196:199], v[100:103], v[48:63]
	ds_read_b64_tr_b16 v[220:221], v171 offset:512
	ds_read_b64_tr_b16 v[222:223], v171 offset:2560
	ds_read_b64_tr_b16 v[224:225], v171 offset:4608
	ds_read_b64_tr_b16 v[226:227], v171 offset:6656
	s_waitcnt lgkmcnt(10)
	v_mfma_f32_32x32x16_bf16 v[0:15], v[104:107], v[148:151], v[0:15]
	s_waitcnt lgkmcnt(8)
	v_mfma_f32_32x32x16_bf16 v[0:15], v[108:111], v[152:155], v[0:15]
	ds_read_b64_tr_b16 v[236:237], v171 offset:8704
	ds_read_b64_tr_b16 v[238:239], v171 offset:10752
	ds_read_b64_tr_b16 v[240:241], v171 offset:12800
	ds_read_b64_tr_b16 v[242:243], v171 offset:14848
	s_waitcnt lgkmcnt(10)
	v_mfma_f32_32x32x16_bf16 v[0:15], v[112:115], v[156:159], v[0:15]
	s_waitcnt lgkmcnt(8)
	v_mfma_f32_32x32x16_bf16 v[0:15], v[116:119], v[216:219], v[0:15]
	s_waitcnt lgkmcnt(6)
	v_mfma_f32_32x32x16_bf16 v[16:31], v[104:107], v[220:223], v[16:31]
	s_waitcnt lgkmcnt(4)
	v_mfma_f32_32x32x16_bf16 v[16:31], v[108:111], v[224:227], v[16:31]
	s_waitcnt lgkmcnt(2)
	v_mfma_f32_32x32x16_bf16 v[16:31], v[112:115], v[236:239], v[16:31]
	s_waitcnt lgkmcnt(0)
	v_mfma_f32_32x32x16_bf16 v[16:31], v[116:119], v[240:243], v[16:31]
	s_barrier
	s_waitcnt vmcnt(0)
	ds_write_b128 v167, v[120:123] offset:39936
	ds_write_b128 v131, v[124:127] offset:49152
	ds_write_b128 v169, v[132:135] offset:39936
	v_exp_f32_e32 v32, v32
	v_exp_f32_e32 v48, v48
	v_exp_f32_e32 v33, v33
	v_exp_f32_e32 v49, v49
	v_exp_f32_e32 v34, v34
	v_exp_f32_e32 v50, v50
	v_exp_f32_e32 v35, v35
	v_exp_f32_e32 v51, v51
	v_exp_f32_e32 v36, v36
	v_exp_f32_e32 v52, v52
	v_exp_f32_e32 v37, v37
	v_exp_f32_e32 v53, v53
	v_exp_f32_e32 v38, v38
	v_exp_f32_e32 v54, v54
	v_exp_f32_e32 v39, v39
	v_exp_f32_e32 v55, v55
	v_exp_f32_e32 v40, v40
	v_exp_f32_e32 v56, v56
	v_exp_f32_e32 v41, v41
	v_exp_f32_e32 v57, v57
	v_exp_f32_e32 v42, v42
	v_exp_f32_e32 v58, v58
	v_exp_f32_e32 v43, v43
	v_exp_f32_e32 v59, v59
	v_exp_f32_e32 v44, v44
	v_exp_f32_e32 v60, v60
	v_exp_f32_e32 v45, v45
	v_exp_f32_e32 v61, v61
	v_exp_f32_e32 v46, v46
	v_exp_f32_e32 v62, v62
	v_exp_f32_e32 v47, v47
	v_exp_f32_e32 v63, v63
	s_waitcnt lgkmcnt(0)
	v_add_f32_e32 v175, v32, v33
	v_add_f32_e32 v174, v48, v49
	v_add_f32_e32 v175, v175, v34
	v_add_f32_e32 v174, v174, v50
	v_add_f32_e32 v175, v175, v35
	v_add_f32_e32 v174, v174, v51
	v_add_f32_e32 v175, v175, v36
	v_add_f32_e32 v174, v174, v52
	v_add_f32_e32 v175, v175, v37
	v_add_f32_e32 v174, v174, v53
	v_add_f32_e32 v175, v175, v38
	v_add_f32_e32 v174, v174, v54
	v_add_f32_e32 v175, v175, v39
	v_add_f32_e32 v174, v174, v55
	v_add_f32_e32 v175, v175, v40
	v_add_f32_e32 v174, v174, v56
	v_add_f32_e32 v175, v175, v41
	v_add_f32_e32 v174, v174, v57
	v_add_f32_e32 v175, v175, v42
	v_add_f32_e32 v174, v174, v58
	v_add_f32_e32 v175, v175, v43
	v_add_f32_e32 v174, v174, v59
	v_add_f32_e32 v175, v175, v44
	v_add_f32_e32 v174, v174, v60
	v_add_f32_e32 v175, v175, v45
	v_add_f32_e32 v174, v174, v61
	v_add_f32_e32 v175, v175, v46
	v_add_f32_e32 v174, v174, v62
	v_add_f32_e32 v175, v175, v47
	v_add_f32_e32 v174, v174, v63
	v_add_f32_e32 v175, v175, v174
	v_cmp_ge_f32_e32 vcc, s23, v175
	s_cmp_eq_u64 vcc, exec
	s_cbranch_scc0 .Lat_rare_t129
; #define SBAR() __builtin_amdgcn_sched_barrier(0)
; #define RESC(a) do { if (__any((a) < 1.f)) { if (hi == 0) al_l[r32] = (a); asm volatile("s_waitcnt lgkmcnt(0)" ::: "memory"); \
;     _Pragma("unroll") for (int dd = 0; dd < 2; ++dd) _Pragma("unroll") for (int r = 0; r < 16; ++r) o[dd][r] *= al_l[crow(r, hi)]; } } while (0)
; __device__ void phase_attn(const Params& p, char* lds) {
;     ...
;     SBAR(); at_qkt(pB0, pB1, K_lds + AT_SHMK, qr, r32, hi, -m_reg);
;     at_finishSM(pA0, pA1, alA, l_reg, pa0, pa1, pa2, pa3); SBAR();
;     pv_d0(o, vb0, pa0, pa1, pa2, pa3); at_partialSM(pB0, pB1, m_reg, alB, false);
;     __syncthreads(); RESC(alB);
.Lat_rare_t129_back:
	v_add_f32_e32 v173, v173, v175
	v_cvt_pk_bf16_f32 v104, v32, v33
	v_cvt_pk_bf16_f32 v105, v34, v35
	v_cvt_pk_bf16_f32 v106, v36, v37
	v_cvt_pk_bf16_f32 v107, v38, v39
	v_cvt_pk_bf16_f32 v108, v40, v41
	v_cvt_pk_bf16_f32 v109, v42, v43
	v_cvt_pk_bf16_f32 v110, v44, v45
	v_cvt_pk_bf16_f32 v111, v46, v47
	v_cvt_pk_bf16_f32 v112, v48, v49
	v_cvt_pk_bf16_f32 v113, v50, v51
	v_cvt_pk_bf16_f32 v114, v52, v53
	v_cvt_pk_bf16_f32 v115, v54, v55
	v_cvt_pk_bf16_f32 v116, v56, v57
	v_cvt_pk_bf16_f32 v117, v58, v59
	v_cvt_pk_bf16_f32 v118, v60, v61
	v_cvt_pk_bf16_f32 v119, v62, v63
	ds_read_b128 v[184:187], v170 offset:26624
	ds_read_b128 v[188:191], v170 offset:33280
	ds_read_b128 v[192:195], v170 offset:26656
	ds_read_b128 v[196:199], v170 offset:33312
	s_barrier
	ds_read_b128 v[200:203], v170 offset:26688
	ds_read_b128 v[204:207], v170 offset:33344
	s_waitcnt lgkmcnt(4)
	v_mfma_f32_32x32x16_bf16 v[32:47], v[184:187], v[80:83], v[64:79]
	v_mfma_f32_32x32x16_bf16 v[48:63], v[188:191], v[80:83], v[64:79]
	ds_read_b128 v[208:211], v170 offset:26720
	ds_read_b128 v[212:215], v170 offset:33376
	s_waitcnt lgkmcnt(4)
	v_mfma_f32_32x32x16_bf16 v[32:47], v[192:195], v[84:87], v[32:47]
	v_mfma_f32_32x32x16_bf16 v[48:63], v[196:199], v[84:87], v[48:63]
	ds_read_b128 v[184:187], v170 offset:26752
	ds_read_b128 v[188:191], v170 offset:33408
	s_waitcnt lgkmcnt(4)
	v_mfma_f32_32x32x16_bf16 v[32:47], v[200:203], v[88:91], v[32:47]
	v_mfma_f32_32x32x16_bf16 v[48:63], v[204:207], v[88:91], v[48:63]
	ds_read_b128 v[192:195], v170 offset:26784
	ds_read_b128 v[196:199], v170 offset:33440
	s_waitcnt lgkmcnt(4)
	v_mfma_f32_32x32x16_bf16 v[32:47], v[208:211], v[92:95], v[32:47]
	v_mfma_f32_32x32x16_bf16 v[48:63], v[212:215], v[92:95], v[48:63]
	ds_read_b64_tr_b16 v[148:149], v171 offset:16384
	ds_read_b64_tr_b16 v[150:151], v171 offset:18432
	ds_read_b64_tr_b16 v[152:153], v171 offset:20480
	ds_read_b64_tr_b16 v[154:155], v171 offset:22528
	s_waitcnt lgkmcnt(6)
	v_mfma_f32_32x32x16_bf16 v[32:47], v[184:187], v[96:99], v[32:47]
	v_mfma_f32_32x32x16_bf16 v[48:63], v[188:191], v[96:99], v[48:63]
	ds_read_b64_tr_b16 v[156:157], v171 offset:24576
	ds_read_b64_tr_b16 v[158:159], v171 offset:26624
	ds_read_b64_tr_b16 v[216:217], v171 offset:28672
	ds_read_b64_tr_b16 v[218:219], v171 offset:30720
	s_waitcnt lgkmcnt(8)
	v_mfma_f32_32x32x16_bf16 v[32:47], v[192:195], v[100:103], v[32:47]
	v_mfma_f32_32x32x16_bf16 v[48:63], v[196:199], v[100:103], v[48:63]
	ds_read_b64_tr_b16 v[220:221], v171 offset:16896
	ds_read_b64_tr_b16 v[222:223], v171 offset:18944
	ds_read_b64_tr_b16 v[224:225], v171 offset:20992
	ds_read_b64_tr_b16 v[226:227], v171 offset:23040
	s_waitcnt lgkmcnt(10)
	v_mfma_f32_32x32x16_bf16 v[0:15], v[104:107], v[148:151], v[0:15]
	s_waitcnt lgkmcnt(8)
	v_mfma_f32_32x32x16_bf16 v[0:15], v[108:111], v[152:155], v[0:15]
	ds_read_b64_tr_b16 v[236:237], v171 offset:25088
	ds_read_b64_tr_b16 v[238:239], v171 offset:27136
	ds_read_b64_tr_b16 v[240:241], v171 offset:29184
	ds_read_b64_tr_b16 v[242:243], v171 offset:31232
	s_waitcnt lgkmcnt(10)
	v_mfma_f32_32x32x16_bf16 v[0:15], v[112:115], v[156:159], v[0:15]
	s_waitcnt lgkmcnt(8)
	v_mfma_f32_32x32x16_bf16 v[0:15], v[116:119], v[216:219], v[0:15]
	s_waitcnt lgkmcnt(6)
	v_mfma_f32_32x32x16_bf16 v[16:31], v[104:107], v[220:223], v[16:31]
	s_waitcnt lgkmcnt(4)
	v_mfma_f32_32x32x16_bf16 v[16:31], v[108:111], v[224:227], v[16:31]
	s_waitcnt lgkmcnt(2)
	v_mfma_f32_32x32x16_bf16 v[16:31], v[112:115], v[236:239], v[16:31]
	s_waitcnt lgkmcnt(0)
	v_mfma_f32_32x32x16_bf16 v[16:31], v[116:119], v[240:243], v[16:31]
	s_barrier
	v_exp_f32_e32 v32, v32
	v_exp_f32_e32 v48, v48
	v_exp_f32_e32 v33, v33
	v_exp_f32_e32 v49, v49
	v_exp_f32_e32 v34, v34
	v_exp_f32_e32 v50, v50
	v_exp_f32_e32 v35, v35
	v_exp_f32_e32 v51, v51
	v_exp_f32_e32 v36, v36
	v_exp_f32_e32 v52, v52
	v_exp_f32_e32 v37, v37
	v_exp_f32_e32 v53, v53
	v_exp_f32_e32 v38, v38
	v_exp_f32_e32 v54, v54
	v_exp_f32_e32 v39, v39
	v_exp_f32_e32 v55, v55
	v_exp_f32_e32 v40, v40
	v_exp_f32_e32 v56, v56
	v_exp_f32_e32 v41, v41
	v_exp_f32_e32 v57, v57
	v_exp_f32_e32 v42, v42
	v_exp_f32_e32 v58, v58
	v_exp_f32_e32 v43, v43
	v_exp_f32_e32 v59, v59
	v_exp_f32_e32 v44, v44
	v_exp_f32_e32 v60, v60
	v_exp_f32_e32 v45, v45
	v_exp_f32_e32 v61, v61
	v_exp_f32_e32 v46, v46
	v_exp_f32_e32 v62, v62
	v_exp_f32_e32 v47, v47
	v_exp_f32_e32 v63, v63
	v_add_f32_e32 v175, v32, v33
	v_add_f32_e32 v174, v48, v49
	v_add_f32_e32 v175, v175, v34
	v_add_f32_e32 v174, v174, v50
	v_add_f32_e32 v175, v175, v35
	v_add_f32_e32 v174, v174, v51
	v_add_f32_e32 v175, v175, v36
	v_add_f32_e32 v174, v174, v52
	v_add_f32_e32 v175, v175, v37
	v_add_f32_e32 v174, v174, v53
	v_add_f32_e32 v175, v175, v38
	v_add_f32_e32 v174, v174, v54
	v_add_f32_e32 v175, v175, v39
	v_add_f32_e32 v174, v174, v55
	v_add_f32_e32 v175, v175, v40
	v_add_f32_e32 v174, v174, v56
	v_add_f32_e32 v175, v175, v41
	v_add_f32_e32 v174, v174, v57
	v_add_f32_e32 v175, v175, v42
	v_add_f32_e32 v174, v174, v58
	v_add_f32_e32 v175, v175, v43
	v_add_f32_e32 v174, v174, v59
	v_add_f32_e32 v175, v175, v44
	v_add_f32_e32 v174, v174, v60
	v_add_f32_e32 v175, v175, v45
	v_add_f32_e32 v174, v174, v61
	v_add_f32_e32 v175, v175, v46
	v_add_f32_e32 v174, v174, v62
	v_add_f32_e32 v175, v175, v47
	v_add_f32_e32 v174, v174, v63
	v_add_f32_e32 v175, v175, v174
	v_cmp_ge_f32_e32 vcc, s23, v175
	s_cmp_eq_u64 vcc, exec
	s_cbranch_scc0 .Lat_rare_t130
; __device__ __forceinline__ void at_finishSM(f32x16& p0, f32x16& p1, float alpha, float& l_reg, bf16x8& pa0, bf16x8& pa1, bf16x8& pa2, bf16x8& pa3) {
; #pragma unroll
;   for (int r = 0; r < 16; ++r) p1[r] = __builtin_amdgcn_exp2f(p1[r]);
;   float ps = 0;
; #pragma unroll
;   for (int r = 0; r < 16; ++r) ps += p0[r];
; #pragma unroll
;   for (int r = 0; r < 16; ++r) ps += p1[r];
;   { auto rr = __builtin_amdgcn_permlane32_swap(__float_as_uint(ps), __float_as_uint(ps), false, false);
;     ps = __uint_as_float(rr[0]) + __uint_as_float(rr[1]); }
;   l_reg = l_reg * alpha + ps;
;     ...
;   PK4(p0, 0, pa0); PK4(p0, 8, pa1); PK4(p1, 0, pa2); PK4(p1, 8, pa3);
;     ...
; }
; __device__ __forceinline__ void at_qkt(f32x16& p0, f32x16& p1, const char* Ks, const bf16x8* qr, int r32, int hi, float negm) {
; #pragma unroll
;   for (int r = 0; r < 16; ++r) { p0[r] = negm; p1[r] = negm; }
; #pragma unroll
;   for (int d0 = 0; d0 < 6; ++d0) {
;     const bf16x8 b0 = *(const bf16x8*)(Ks + r32 * AT_KROW + d0 * 32 + hi * 16);
;     const bf16x8 b1 = *(const bf16x8*)(Ks + (32 + r32) * AT_KROW + d0 * 32 + hi * 16);
;     p0 = MFMA(b0, qr[d0], p0);
;     p1 = MFMA(b1, qr[d0], p1);
;   }
; }
; __device__ __forceinline__ int v_st(int k, int c) { const int kk = (k & ~0xC) | ((k & 4) << 1) | ((k & 8) >> 1); return ((kk >> 3) * 4 + (c >> 5)) * 512 + ((kk & 7) * 32 + (c & 31)) * 2; }
; __device__ __forceinline__ int v_rd_base(int lane) { return ((lane & 3) << 3) | (((lane >> 2) & 3) << 6) | (((lane >> 4) & 1) << 5) | (((lane >> 5) & 1) << 8); }
; template <int OFF> __device__ __forceinline__ s16x4 tr_read(int vb) {
;   s16x4 r; asm volatile("ds_read_b64_tr_b16 %0, %1 offset:%2" : "=&v"(r) : "v"(vb), "i"(OFF) : "memory"); return r;
; }
; template <int D0> __device__ __forceinline__ void pv_one(f32x16& od, int vb, bf16x8 pa0, bf16x8 pa1, bf16x8 pa2, bf16x8 pa3) {
;   const s16x4 l0 = tr_read<v_rd_off(D0, 0, 0)>(vb), h0 = tr_read<v_rd_off(D0, 0, 1)>(vb), l1 = tr_read<v_rd_off(D0, 1, 0)>(vb), h1 = tr_read<v_rd_off(D0, 1, 1)>(vb);
;   const s16x4 l2 = tr_read<v_rd_off(D0, 2, 0)>(vb), h2 = tr_read<v_rd_off(D0, 2, 1)>(vb), l3 = tr_read<v_rd_off(D0, 3, 0)>(vb), h3 = tr_read<v_rd_off(D0, 3, 1)>(vb);
;   asm volatile("s_waitcnt lgkmcnt(0)" ::: "memory"); SBAR();
;     ...
;   od = MFMA(pa0, PK(l0, h0), od);
;   od = MFMA(pa1, PK(l1, h1), od);
;   od = MFMA(pa2, PK(l2, h2), od);
;   od = MFMA(pa3, PK(l3, h3), od);
;     ...
; }
.Lat_rare_t130_back:
	v_add_f32_e32 v173, v173, v175
	v_cvt_pk_bf16_f32 v104, v32, v33
	v_cvt_pk_bf16_f32 v105, v34, v35
	v_cvt_pk_bf16_f32 v106, v36, v37
	v_cvt_pk_bf16_f32 v107, v38, v39
	v_cvt_pk_bf16_f32 v108, v40, v41
	v_cvt_pk_bf16_f32 v109, v42, v43
	v_cvt_pk_bf16_f32 v110, v44, v45
	v_cvt_pk_bf16_f32 v111, v46, v47
	v_cvt_pk_bf16_f32 v112, v48, v49
	v_cvt_pk_bf16_f32 v113, v50, v51
	v_cvt_pk_bf16_f32 v114, v52, v53
	v_cvt_pk_bf16_f32 v115, v54, v55
	v_cvt_pk_bf16_f32 v116, v56, v57
	v_cvt_pk_bf16_f32 v117, v58, v59
	v_cvt_pk_bf16_f32 v118, v60, v61
	v_cvt_pk_bf16_f32 v119, v62, v63
	ds_read_b128 v[184:187], v170 offset:39936
	ds_read_b128 v[188:191], v170 offset:46592
	ds_read_b128 v[192:195], v170 offset:39968
	ds_read_b128 v[196:199], v170 offset:46624
	s_barrier
	ds_read_b128 v[200:203], v170 offset:40000
	ds_read_b128 v[204:207], v170 offset:46656
	s_waitcnt lgkmcnt(4)
	v_mfma_f32_32x32x16_bf16 v[32:47], v[184:187], v[80:83], v[64:79]
	v_mfma_f32_32x32x16_bf16 v[48:63], v[188:191], v[80:83], v[64:79]
	ds_read_b128 v[208:211], v170 offset:40032
	ds_read_b128 v[212:215], v170 offset:46688
	s_waitcnt lgkmcnt(4)
	v_mfma_f32_32x32x16_bf16 v[32:47], v[192:195], v[84:87], v[32:47]
	v_mfma_f32_32x32x16_bf16 v[48:63], v[196:199], v[84:87], v[48:63]
	ds_read_b128 v[184:187], v170 offset:40064
	ds_read_b128 v[188:191], v170 offset:46720
	s_waitcnt lgkmcnt(4)
	v_mfma_f32_32x32x16_bf16 v[32:47], v[200:203], v[88:91], v[32:47]
	v_mfma_f32_32x32x16_bf16 v[48:63], v[204:207], v[88:91], v[48:63]
	ds_read_b128 v[192:195], v170 offset:40096
	ds_read_b128 v[196:199], v170 offset:46752
	s_waitcnt lgkmcnt(4)
	v_mfma_f32_32x32x16_bf16 v[32:47], v[208:211], v[92:95], v[32:47]
	v_mfma_f32_32x32x16_bf16 v[48:63], v[212:215], v[92:95], v[48:63]
	ds_read_b64_tr_b16 v[148:149], v171 offset:32768
	ds_read_b64_tr_b16 v[150:151], v171 offset:34816
	ds_read_b64_tr_b16 v[152:153], v171 offset:36864
	ds_read_b64_tr_b16 v[154:155], v171 offset:38912
	s_waitcnt lgkmcnt(6)
	v_mfma_f32_32x32x16_bf16 v[32:47], v[184:187], v[96:99], v[32:47]
	v_mfma_f32_32x32x16_bf16 v[48:63], v[188:191], v[96:99], v[48:63]
	ds_read_b64_tr_b16 v[156:157], v171 offset:40960
	ds_read_b64_tr_b16 v[158:159], v171 offset:43008
	ds_read_b64_tr_b16 v[216:217], v171 offset:45056
	ds_read_b64_tr_b16 v[218:219], v171 offset:47104
	s_waitcnt lgkmcnt(8)
	v_mfma_f32_32x32x16_bf16 v[32:47], v[192:195], v[100:103], v[32:47]
	v_mfma_f32_32x32x16_bf16 v[48:63], v[196:199], v[100:103], v[48:63]
	ds_read_b64_tr_b16 v[220:221], v171 offset:33280
	ds_read_b64_tr_b16 v[222:223], v171 offset:35328
	ds_read_b64_tr_b16 v[224:225], v171 offset:37376
	ds_read_b64_tr_b16 v[226:227], v171 offset:39424
	s_waitcnt lgkmcnt(10)
	v_mfma_f32_32x32x16_bf16 v[0:15], v[104:107], v[148:151], v[0:15]
	s_waitcnt lgkmcnt(8)
	v_mfma_f32_32x32x16_bf16 v[0:15], v[108:111], v[152:155], v[0:15]
	ds_read_b64_tr_b16 v[236:237], v171 offset:41472
	ds_read_b64_tr_b16 v[238:239], v171 offset:43520
	ds_read_b64_tr_b16 v[240:241], v171 offset:45568
	ds_read_b64_tr_b16 v[242:243], v171 offset:47616
	s_waitcnt lgkmcnt(10)
	v_mfma_f32_32x32x16_bf16 v[0:15], v[112:115], v[156:159], v[0:15]
	s_waitcnt lgkmcnt(8)
	v_mfma_f32_32x32x16_bf16 v[0:15], v[116:119], v[216:219], v[0:15]
	s_waitcnt lgkmcnt(6)
	v_mfma_f32_32x32x16_bf16 v[16:31], v[104:107], v[220:223], v[16:31]
	s_waitcnt lgkmcnt(4)
	v_mfma_f32_32x32x16_bf16 v[16:31], v[108:111], v[224:227], v[16:31]
	s_waitcnt lgkmcnt(2)
	v_mfma_f32_32x32x16_bf16 v[16:31], v[112:115], v[236:239], v[16:31]
	s_waitcnt lgkmcnt(0)
	v_mfma_f32_32x32x16_bf16 v[16:31], v[116:119], v[240:243], v[16:31]
	s_barrier
	v_exp_f32_e32 v32, v32
	v_exp_f32_e32 v48, v48
	v_exp_f32_e32 v33, v33
	v_exp_f32_e32 v49, v49
	v_exp_f32_e32 v34, v34
	v_exp_f32_e32 v50, v50
	v_exp_f32_e32 v35, v35
	v_exp_f32_e32 v51, v51
	v_exp_f32_e32 v36, v36
	v_exp_f32_e32 v52, v52
	v_exp_f32_e32 v37, v37
	v_exp_f32_e32 v53, v53
	v_exp_f32_e32 v38, v38
	v_exp_f32_e32 v54, v54
	v_exp_f32_e32 v39, v39
	v_exp_f32_e32 v55, v55
	v_exp_f32_e32 v40, v40
	v_exp_f32_e32 v56, v56
	v_exp_f32_e32 v41, v41
	v_exp_f32_e32 v57, v57
	v_exp_f32_e32 v42, v42
	v_exp_f32_e32 v58, v58
	v_exp_f32_e32 v43, v43
	v_exp_f32_e32 v59, v59
	v_exp_f32_e32 v44, v44
	v_exp_f32_e32 v60, v60
	v_exp_f32_e32 v45, v45
	v_exp_f32_e32 v61, v61
	v_exp_f32_e32 v46, v46
	v_exp_f32_e32 v62, v62
	v_exp_f32_e32 v47, v47
	v_exp_f32_e32 v63, v63
	v_add_f32_e32 v175, v32, v33
	v_add_f32_e32 v174, v48, v49
	v_add_f32_e32 v175, v175, v34
	v_add_f32_e32 v174, v174, v50
	v_add_f32_e32 v175, v175, v35
	v_add_f32_e32 v174, v174, v51
	v_add_f32_e32 v175, v175, v36
	v_add_f32_e32 v174, v174, v52
	v_add_f32_e32 v175, v175, v37
	v_add_f32_e32 v174, v174, v53
	v_add_f32_e32 v175, v175, v38
	v_add_f32_e32 v174, v174, v54
	v_add_f32_e32 v175, v175, v39
	v_add_f32_e32 v174, v174, v55
	v_add_f32_e32 v175, v175, v40
	v_add_f32_e32 v174, v174, v56
	v_add_f32_e32 v175, v175, v41
	v_add_f32_e32 v174, v174, v57
	v_add_f32_e32 v175, v175, v42
	v_add_f32_e32 v174, v174, v58
	v_add_f32_e32 v175, v175, v43
	v_add_f32_e32 v174, v174, v59
	v_add_f32_e32 v175, v175, v44
	v_add_f32_e32 v174, v174, v60
	v_add_f32_e32 v175, v175, v45
	v_add_f32_e32 v174, v174, v61
	v_add_f32_e32 v175, v175, v46
	v_add_f32_e32 v174, v174, v62
	v_add_f32_e32 v175, v175, v47
	v_add_f32_e32 v174, v174, v63
	v_add_f32_e32 v175, v175, v174
	v_cmp_ge_f32_e32 vcc, s23, v175
	s_cmp_eq_u64 vcc, exec
	s_cbranch_scc0 .Lat_rare_t131
